# GLA loops: prefetch retired at the end-of-unit register hand-over (on top of the earlier stack)
# speedup vs baseline: 1.0109x; 1.0109x over previous
; #define LAS __attribute__((address_space(3)))
; __device__ __forceinline__ unsigned pk2(float lo, float hi) { return f2bf(lo) | (f2bf(hi) << 16); }
; #define LBAR() do { asm volatile("s_waitcnt lgkmcnt(0)" ::: "memory"); __builtin_amdgcn_s_barrier(); asm volatile("" ::: "memory"); } while (0)
; __device__ __forceinline__ void g1_unit(const GPre& R, bf16* __restrict__ STATE, float* __restrict__ DEC, int n, int h, LAS char* lds) {
;     ...
;   { const LAS float* Bf = (const LAS float*)(lds + L_BD); const LAS float* Bb = Bf + 64 * GS;
;     float kef[8], keb[8];
; #pragma unroll
;     for (int j = 0; j < 8; ++j) { const int d = dg * 8 + j; const float kv = (j & 1) ? bfhi(kk[j >> 1]) : bflo(kk[j >> 1]);
;       const float bl = Bf[63 * GS + d], b0 = Bb[d];
;       kef[j] = kv * __builtin_amdgcn_exp2f(bl - Bf[s * GS + d]); keb[j] = kv * __builtin_amdgcn_exp2f(b0 - Bb[s * GS + d]);
;       if (s == 0) { DEC[((size_t)(0 * NCHUNK + n) * 4 + h) * 64 + d] = __builtin_amdgcn_exp2f(bl); DEC[((size_t)(1 * NCHUNK + n) * 4 + h) * 64 + d] = __builtin_amdgcn_exp2f(b0); } }
;     v4u w;
;     w.x = pk2(kef[0], kef[1]); w.y = pk2(kef[2], kef[3]); w.z = pk2(kef[4], kef[5]); w.w = pk2(kef[6], kef[7]); *(LAS v4u*)(lds + L_KTF + (s * ST72 + dg * 8) * 2) = w;
;     w.x = pk2(keb[0], keb[1]); w.y = pk2(keb[2], keb[3]); w.z = pk2(keb[4], keb[5]); w.w = pk2(keb[6], keb[7]); *(LAS v4u*)(lds + L_KTB + (s * ST72 + dg * 8) * 2) = w; }
;   LBAR();
;   const int dt = wid >> 2, et = wid & 3, r32 = lane & 31, hi = lane >> 5;
; #pragma unroll
;   for (int dir = 0; dir < 2; ++dir) { f32x16 acc = {};
; #pragma unroll
;     for (int ks = 0; ks < 4; ++ks) acc = __builtin_amdgcn_mfma_f32_32x32x16_bf16(trfrag(lds + (dir ? L_KTB : L_KTF), ST72 * 2, 16 * ks, 32 * dt, lane), trfrag(lds + L_V, VS, 16 * ks, 32 * et, lane), acc, 0, 0, 0);
.LBB0_198:
	s_or_b64 exec, exec, s[50:51]
	s_waitcnt lgkmcnt(14)
	v_sub_f32_e32 v1, v1, v3
	v_exp_f32_e32 v70, v1
	s_waitcnt lgkmcnt(12)
	v_sub_f32_e32 v1, v5, v7
	v_exp_f32_e32 v72, v1
	s_waitcnt lgkmcnt(10)
	v_sub_f32_e32 v1, v11, v13
	v_exp_f32_e32 v71, v1
	s_waitcnt lgkmcnt(8)
	v_sub_f32_e32 v1, v15, v21
	v_exp_f32_e32 v73, v1
	s_waitcnt lgkmcnt(6)
	v_sub_f32_e32 v1, v23, v25
	v_exp_f32_e32 v74, v1
	s_waitcnt lgkmcnt(4)
	v_sub_f32_e32 v1, v27, v29
	v_exp_f32_e32 v76, v1
	s_waitcnt lgkmcnt(2)
	v_sub_f32_e32 v1, v31, v65
	v_exp_f32_e32 v75, v1
	s_waitcnt lgkmcnt(0)
	v_sub_f32_e32 v1, v67, v9
	v_exp_f32_e32 v77, v1
	v_sub_f32_e32 v1, v4, v6
	v_sub_f32_e32 v3, v14, v20
	v_sub_f32_e32 v5, v26, v28
	v_sub_f32_e32 v7, v66, v8
	v_sub_f32_e32 v0, v0, v2
	v_exp_f32_e32 v2, v1
	v_exp_f32_e32 v3, v3
	v_sub_f32_e32 v4, v22, v24
	v_exp_f32_e32 v6, v5
	v_sub_f32_e32 v5, v30, v64
	v_exp_f32_e32 v7, v7
	v_exp_f32_e32 v4, v4
	v_exp_f32_e32 v5, v5
	v_sub_f32_e32 v1, v10, v12
	v_exp_f32_e32 v0, v0
	v_exp_f32_e32 v1, v1
	v_and_b32_e32 v11, 0xffff0000, v17
	v_and_b32_e32 v10, 0xffff0000, v16
	v_and_b32_e32 v15, 0xffff0000, v19
	v_and_b32_e32 v14, 0xffff0000, v18
	v_pk_mul_f32 v[2:3], v[2:3], v[10:11]
	v_lshlrev_b32_e32 v13, 16, v19
	v_lshlrev_b32_e32 v12, 16, v18
	v_pk_mul_f32 v[6:7], v[6:7], v[14:15]
	v_lshlrev_b32_e32 v9, 16, v17
	v_lshlrev_b32_e32 v8, 16, v16
	v_pk_mul_f32 v[4:5], v[4:5], v[12:13]
	v_bfe_u32 v16, v7, 16, 1
	v_bfe_u32 v17, v6, 16, 1
	v_bfe_u32 v18, v3, 16, 1
	v_bfe_u32 v19, v2, 16, 1
	v_add3_u32 v19, v2, v19, s65
	v_add3_u32 v18, v3, v18, s65
	v_add3_u32 v2, v6, v17, s65
	v_add3_u32 v3, v7, v16, s65
	v_bfe_u32 v16, v4, 16, 1
	v_bfe_u32 v17, v5, 16, 1
	v_pk_mul_f32 v[0:1], v[0:1], v[8:9]
	v_add3_u32 v5, v5, v17, s65
	v_add3_u32 v4, v4, v16, s65
	v_bfe_u32 v6, v0, 16, 1
	v_bfe_u32 v7, v1, 16, 1
	v_lshrrev_b32_e32 v4, 16, v4
	v_lshrrev_b32_e32 v5, 16, v5
	v_add3_u32 v1, v1, v7, s65
	v_add3_u32 v0, v0, v6, s65
	v_and_or_b32 v3, v3, s64, v5
	v_and_or_b32 v2, v2, s64, v4
	v_lshlrev_b32_e32 v4, 4, v69
	v_mul_lo_u32 v5, v68, s72
	v_lshrrev_b32_e32 v0, 16, v0
	v_lshrrev_b32_e32 v1, 16, v1
	v_add3_u32 v16, v4, v5, 0
	v_and_or_b32 v1, v18, s64, v1
	v_and_or_b32 v0, v19, s64, v0
	v_add_u32_e32 v4, 0x19c00, v16
	ds_write_b128 v4, v[0:3]
	v_pk_mul_f32 v[2:3], v[72:73], v[10:11]
	v_pk_mul_f32 v[6:7], v[76:77], v[14:15]
	v_pk_mul_f32 v[0:1], v[70:71], v[8:9]
	v_pk_mul_f32 v[4:5], v[74:75], v[12:13]
	v_bfe_u32 v8, v7, 16, 1
	v_bfe_u32 v9, v6, 16, 1
	v_bfe_u32 v10, v3, 16, 1
	v_bfe_u32 v11, v2, 16, 1
	v_add3_u32 v11, v2, v11, s65
	v_add3_u32 v10, v3, v10, s65
	v_add3_u32 v2, v6, v9, s65
	v_add3_u32 v3, v7, v8, s65
	v_bfe_u32 v6, v0, 16, 1
	v_bfe_u32 v7, v1, 16, 1
	v_bfe_u32 v8, v4, 16, 1
	v_bfe_u32 v9, v5, 16, 1
	v_add3_u32 v5, v5, v9, s65
	v_add3_u32 v4, v4, v8, s65
	v_add3_u32 v1, v1, v7, s65
	v_add3_u32 v0, v0, v6, s65
	v_lshrrev_b32_e32 v0, 16, v0
	v_lshrrev_b32_e32 v1, 16, v1
	v_lshrrev_b32_e32 v4, 16, v4
	v_lshrrev_b32_e32 v5, 16, v5
	v_and_or_b32 v3, v3, s64, v5
	v_and_or_b32 v2, v2, s64, v4
	v_and_or_b32 v1, v10, s64, v1
	v_and_or_b32 v0, v11, s64, v0
	v_add_u32_e32 v4, 0x1c000, v16
	ds_write_b128 v4, v[0:3]
	s_ashr_i32 s30, s6, 8
	v_lshrrev_b32_e32 v0, 2, v80
	v_lshlrev_b32_e32 v1, 2, v80
	s_lshl_b32 s31, s30, 5
	v_and_b32_e32 v28, 11, v0
	v_and_b32_e32 v0, 16, v80
	v_and_b32_e32 v1, 12, v1
	s_lshr_b32 s6, s6, 1
	v_or3_b32 v2, s31, v0, v1
	s_and_b32 s6, s6, 0x60
	v_lshl_add_u32 v29, v2, 1, 0
	v_or3_b32 v0, v0, s6, v1
	v_lshlrev_b32_e32 v4, 1, v0
	v_add_u32_e32 v24, 0x19c00, v29
	v_mul_u32_u24_e32 v5, 0x110, v28
	s_waitcnt lgkmcnt(0)
	s_barrier
	v_mad_u32_u24 v2, v28, s72, v24
	v_add3_u32 v30, 0, v4, v5
	ds_read_b64_tr_b16 v[0:1], v2
	ds_read_b64_tr_b16 v[2:3], v2 offset:576
	ds_read_b64_tr_b16 v[16:17], v30 offset:34816
	ds_read_b64_tr_b16 v[18:19], v30 offset:35904
	s_waitcnt lgkmcnt(0)
	v_mfma_f32_32x32x16_bf16 v[0:15], v[0:3], v[16:19], 0
	v_mad_u32_u24 v31, v28, s72, v126
	v_add_u32_e32 v22, v24, v31
	ds_read_b64_tr_b16 v[20:21], v22
	ds_read_b64_tr_b16 v[22:23], v22 offset:576
	ds_read_b64_tr_b16 v[64:65], v30 offset:39168
	ds_read_b64_tr_b16 v[66:67], v30 offset:40256
	ds_read_b64_tr_b16 v[68:69], v30 offset:43520
	ds_read_b64_tr_b16 v[70:71], v30 offset:44608
	ds_read_b64_tr_b16 v[74:75], v30 offset:48960
	v_mad_u32_u24 v90, v28, s72, v127
	v_mad_u32_u24 v91, v28, s72, v128
	v_add_u32_e32 v26, v24, v91
	s_lshl_b32 s31, s33, 14
	s_waitcnt lgkmcnt(3)
	v_mfma_f32_32x32x16_bf16 v[0:15], v[20:23], v[64:67], v[0:15]
	v_add_u32_e32 v22, v24, v90
	ds_read_b64_tr_b16 v[20:21], v22
	ds_read_b64_tr_b16 v[22:23], v22 offset:576
	ds_read_b64_tr_b16 v[24:25], v26
	ds_read_b64_tr_b16 v[26:27], v26 offset:576
	ds_read_b64_tr_b16 v[72:73], v30 offset:47872
	s_add_u32 s31, s68, s31
	s_addc_u32 s33, s69, 0
	s_lshl_b64 s[28:29], s[28:29], 16
	s_waitcnt lgkmcnt(3)
	v_mfma_f32_32x32x16_bf16 v[0:15], v[20:23], v[68:71], v[0:15]
	v_and_b32_e32 v20, 31, v80
	v_lshl_or_b32 v20, s30, 12, v20
	s_add_u32 s28, s31, s28
	s_addc_u32 s29, s33, s29
	s_lshl_b64 s[0:1], s[0:1], 16
	s_add_u32 s0, s31, s0
	s_addc_u32 s1, s33, s1
	s_waitcnt lgkmcnt(0)
; #define LAS __attribute__((address_space(3)))
; __device__ __forceinline__ unsigned f2bf(float f) { unsigned u = __builtin_bit_cast(unsigned, f); return (u + 0x7fffu + ((u >> 16) & 1u)) >> 16; }
; __device__ __forceinline__ int crow(int r, int hi) { return (r & 3) + 8 * (r >> 2) + 4 * hi; }
; #define LBAR() do { asm volatile("s_waitcnt lgkmcnt(0)" ::: "memory"); __builtin_amdgcn_s_barrier(); asm volatile("" ::: "memory"); } while (0)
; __device__ __forceinline__ void g1_unit(const GPre& R, bf16* __restrict__ STATE, float* __restrict__ DEC, int n, int h, LAS char* lds) {
;     ...
;   for (int dir = 0; dir < 2; ++dir) { f32x16 acc = {};
; #pragma unroll
;     for (int ks = 0; ks < 4; ++ks) acc = __builtin_amdgcn_mfma_f32_32x32x16_bf16(trfrag(lds + (dir ? L_KTB : L_KTF), ST72 * 2, 16 * ks, 32 * dt, lane), trfrag(lds + L_V, VS, 16 * ks, 32 * et, lane), acc, 0, 0, 0);
;     bf16* So = STATE + ((size_t)(dir * NCHUNK + n) * 4 + h) * 8192;
; #pragma unroll
;     for (int r = 0; r < 16; ++r) So[(32 * dt + crow(r, hi)) * 128 + 32 * et + r32] = (bf16)f2bf(acc[r]); }
;   LBAR();
; __global__ void __launch_bounds__(NWAVES * 64, 2) hymba_fwd(Args args) {
;     ...
;       for (; u < NCHUNK * 4; u += G) { const int un = u + G;
;         if (un < NCHUNK * 4) gla::load_pre<false>(nxt, PROJ, args, WGT, STATE, un >> 2, un & 3);
;         gla::g1_unit(cur, STATE, DEC, u >> 2, u & 3, (LAS char*)ldsl); cur = nxt; } }
	v_mfma_f32_32x32x16_bf16 v[0:15], v[24:27], v[72:75], v[0:15]
	s_add_i32 s3, s3, s15
	s_andn2_b64 vcc, exec, s[26:27]
	s_mov_b32 s30, s73
	s_nop 8
	v_bfe_u32 v21, v0, 16, 1
	v_add3_u32 v0, v0, v21, s65
	v_lshlrev_b32_e32 v21, 4, v80
	v_and_b32_e32 v21, 0x200, v21
	v_or3_b32 v76, v20, v21, s6
	v_ashrrev_i32_e32 v77, 31, v76
	v_lshlrev_b64 v[78:79], 1, v[76:77]
	v_lshl_add_u64 v[20:21], s[28:29], 0, v[78:79]
	global_store_short_d16_hi v[20:21], v0, off
	v_bfe_u32 v0, v1, 16, 1
	v_add3_u32 v0, v1, v0, s65
	global_store_short_d16_hi v[20:21], v0, off offset:256
	v_bfe_u32 v0, v2, 16, 1
	v_add3_u32 v0, v2, v0, s65
	global_store_short_d16_hi v[20:21], v0, off offset:512
	v_bfe_u32 v0, v3, 16, 1
	v_add3_u32 v0, v3, v0, s65
	global_store_short_d16_hi v[20:21], v0, off offset:768
	v_bfe_u32 v0, v4, 16, 1
	v_add3_u32 v0, v4, v0, s65
	global_store_short_d16_hi v[20:21], v0, off offset:2048
	v_bfe_u32 v0, v5, 16, 1
	v_add3_u32 v0, v5, v0, s65
	global_store_short_d16_hi v[20:21], v0, off offset:2304
	v_bfe_u32 v0, v6, 16, 1
	v_add3_u32 v0, v6, v0, s65
	global_store_short_d16_hi v[20:21], v0, off offset:2560
	v_bfe_u32 v0, v7, 16, 1
	v_add3_u32 v0, v7, v0, s65
	global_store_short_d16_hi v[20:21], v0, off offset:2816
	v_bfe_u32 v0, v8, 16, 1
	v_add3_u32 v2, v8, v0, s65
	v_or_b32_e32 v0, 0x800, v76
	v_ashrrev_i32_e32 v1, 31, v0
	v_lshlrev_b64 v[82:83], 1, v[0:1]
	v_lshl_add_u64 v[0:1], s[28:29], 0, v[82:83]
	global_store_short_d16_hi v[0:1], v2, off
	v_bfe_u32 v0, v9, 16, 1
	v_add3_u32 v2, v9, v0, s65
	v_or_b32_e32 v0, 0x880, v76
	v_ashrrev_i32_e32 v1, 31, v0
	v_lshlrev_b64 v[8:9], 1, v[0:1]
	v_lshl_add_u64 v[0:1], s[28:29], 0, v[8:9]
	global_store_short_d16_hi v[0:1], v2, off
	v_bfe_u32 v0, v10, 16, 1
	v_add3_u32 v2, v10, v0, s65
	v_or_b32_e32 v0, 0x900, v76
	v_ashrrev_i32_e32 v1, 31, v0
	v_lshlrev_b64 v[84:85], 1, v[0:1]
	v_lshl_add_u64 v[0:1], s[28:29], 0, v[84:85]
	global_store_short_d16_hi v[0:1], v2, off
	v_bfe_u32 v0, v11, 16, 1
	v_add3_u32 v2, v11, v0, s65
	v_or_b32_e32 v0, 0x980, v76
	v_ashrrev_i32_e32 v1, 31, v0
	v_lshlrev_b64 v[10:11], 1, v[0:1]
	v_lshl_add_u64 v[0:1], s[28:29], 0, v[10:11]
	global_store_short_d16_hi v[0:1], v2, off
	v_bfe_u32 v0, v12, 16, 1
	v_add3_u32 v2, v12, v0, s65
	v_or_b32_e32 v0, 0xc00, v76
	v_ashrrev_i32_e32 v1, 31, v0
	v_lshlrev_b64 v[86:87], 1, v[0:1]
	v_lshl_add_u64 v[0:1], s[28:29], 0, v[86:87]
	v_add_u32_e32 v77, 0x1c000, v29
	global_store_short_d16_hi v[0:1], v2, off
	v_mad_u32_u24 v2, v28, s72, v77
	ds_read_b64_tr_b16 v[0:1], v2
	ds_read_b64_tr_b16 v[2:3], v2 offset:576
	v_bfe_u32 v4, v13, 16, 1
	v_add_u32_e32 v6, v77, v31
	s_waitcnt lgkmcnt(0)
	v_mfma_f32_32x32x16_bf16 v[16:31], v[0:3], v[16:19], 0
	v_add3_u32 v80, v13, v4, s65
	v_or_b32_e32 v4, 0xc80, v76
	v_ashrrev_i32_e32 v5, 31, v4
	v_lshlrev_b64 v[12:13], 1, v[4:5]
	ds_read_b64_tr_b16 v[4:5], v6
	ds_read_b64_tr_b16 v[6:7], v6 offset:576
	v_lshl_add_u64 v[88:89], s[28:29], 0, v[12:13]
	global_store_short_d16_hi v[88:89], v80, off
	s_waitcnt lgkmcnt(0)
	v_mfma_f32_32x32x16_bf16 v[16:31], v[4:7], v[64:67], v[16:31]
	v_bfe_u32 v0, v14, 16, 1
	v_add_u32_e32 v2, v77, v90
	v_add3_u32 v14, v14, v0, s65
	ds_read_b64_tr_b16 v[0:1], v2
	ds_read_b64_tr_b16 v[2:3], v2 offset:576
	v_or_b32_e32 v88, 0xd00, v76
	v_ashrrev_i32_e32 v89, 31, v88
	v_lshlrev_b64 v[64:65], 1, v[88:89]
	s_waitcnt lgkmcnt(0)
	v_mfma_f32_32x32x16_bf16 v[16:31], v[0:3], v[68:71], v[16:31]
	v_lshl_add_u64 v[4:5], s[28:29], 0, v[64:65]
	global_store_short_d16_hi v[4:5], v14, off
	v_add_u32_e32 v6, v77, v91
	ds_read_b64_tr_b16 v[4:5], v6
	ds_read_b64_tr_b16 v[6:7], v6 offset:576
	v_bfe_u32 v0, v15, 16, 1
	v_add3_u32 v14, v15, v0, s65
	v_or_b32_e32 v0, 0xd80, v76
	s_waitcnt lgkmcnt(0)
	v_mfma_f32_32x32x16_bf16 v[16:31], v[4:7], v[72:75], v[16:31]
	v_ashrrev_i32_e32 v1, 31, v0
	v_lshlrev_b64 v[0:1], 1, v[0:1]
	v_lshl_add_u64 v[2:3], s[28:29], 0, v[0:1]
	global_store_short_d16_hi v[2:3], v14, off
	v_lshl_add_u64 v[0:1], s[0:1], 0, v[0:1]
	s_nop 6
	v_bfe_u32 v2, v16, 16, 1
	v_add3_u32 v4, v16, v2, s65
	v_lshl_add_u64 v[2:3], s[0:1], 0, v[78:79]
	global_store_short_d16_hi v[2:3], v4, off
	v_bfe_u32 v4, v17, 16, 1
	v_add3_u32 v4, v17, v4, s65
	global_store_short_d16_hi v[2:3], v4, off offset:256
	v_bfe_u32 v4, v18, 16, 1
	v_add3_u32 v4, v18, v4, s65
	global_store_short_d16_hi v[2:3], v4, off offset:512
	v_bfe_u32 v4, v19, 16, 1
	v_add3_u32 v4, v19, v4, s65
	global_store_short_d16_hi v[2:3], v4, off offset:768
	v_bfe_u32 v4, v20, 16, 1
	v_add3_u32 v4, v20, v4, s65
	global_store_short_d16_hi v[2:3], v4, off offset:2048
	v_bfe_u32 v4, v21, 16, 1
	v_add3_u32 v4, v21, v4, s65
	global_store_short_d16_hi v[2:3], v4, off offset:2304
	v_bfe_u32 v4, v22, 16, 1
	v_add3_u32 v4, v22, v4, s65
	global_store_short_d16_hi v[2:3], v4, off offset:2560
	v_bfe_u32 v4, v23, 16, 1
	v_add3_u32 v4, v23, v4, s65
	global_store_short_d16_hi v[2:3], v4, off offset:2816
	v_bfe_u32 v2, v24, 16, 1
	v_add3_u32 v4, v24, v2, s65
	v_lshl_add_u64 v[2:3], s[0:1], 0, v[82:83]
	global_store_short_d16_hi v[2:3], v4, off
	v_bfe_u32 v2, v25, 16, 1
	v_add3_u32 v4, v25, v2, s65
	v_lshl_add_u64 v[2:3], s[0:1], 0, v[8:9]
	global_store_short_d16_hi v[2:3], v4, off
	v_bfe_u32 v2, v26, 16, 1
	v_add3_u32 v4, v26, v2, s65
	v_lshl_add_u64 v[2:3], s[0:1], 0, v[84:85]
	global_store_short_d16_hi v[2:3], v4, off
	v_bfe_u32 v2, v27, 16, 1
	v_add3_u32 v4, v27, v2, s65
	v_lshl_add_u64 v[2:3], s[0:1], 0, v[10:11]
	global_store_short_d16_hi v[2:3], v4, off
	v_bfe_u32 v2, v28, 16, 1
	v_add3_u32 v4, v28, v2, s65
	v_lshl_add_u64 v[2:3], s[0:1], 0, v[86:87]
	global_store_short_d16_hi v[2:3], v4, off
	v_bfe_u32 v2, v29, 16, 1
	v_add3_u32 v4, v29, v2, s65
	v_lshl_add_u64 v[2:3], s[0:1], 0, v[12:13]
	global_store_short_d16_hi v[2:3], v4, off
	v_bfe_u32 v2, v30, 16, 1
	v_add3_u32 v4, v30, v2, s65
	v_lshl_add_u64 v[2:3], s[0:1], 0, v[64:65]
	global_store_short_d16_hi v[2:3], v4, off
	v_bfe_u32 v2, v31, 16, 1
	v_add3_u32 v2, v31, v2, s65
	global_store_short_d16_hi v[0:1], v2, off
	s_waitcnt lgkmcnt(0)
	s_barrier
	s_waitcnt vmcnt(32)
	v_mov_b64_e32 v[20:21], v[48:49]
	v_mov_b64_e32 v[24:25], v[56:57]
	v_mov_b64_e32 v[28:29], v[60:61]
	v_mov_b64_e32 v[0:1], v[44:45]
	v_mov_b64_e32 v[4:5], v[40:41]
	v_mov_b64_e32 v[8:9], v[36:37]
	v_mov_b64_e32 v[12:13], v[32:33]
	v_mov_b64_e32 v[16:17], v[52:53]
	v_mov_b32_e32 v84, v130
	v_mov_b64_e32 v[22:23], v[50:51]
	v_mov_b64_e32 v[26:27], v[58:59]
	v_mov_b64_e32 v[30:31], v[62:63]
	v_mov_b64_e32 v[2:3], v[46:47]
	v_mov_b64_e32 v[6:7], v[42:43]
	v_mov_b64_e32 v[10:11], v[38:39]
	v_mov_b64_e32 v[14:15], v[34:35]
	v_mov_b64_e32 v[18:19], v[54:55]
	s_cbranch_vccz .LBB0_233

; #define LAS __attribute__((address_space(3)))
; __device__ __forceinline__ void g1_unit(const GPre& R, bf16* __restrict__ STATE, float* __restrict__ DEC, int n, int h, LAS char* lds) {
;     ...
;   { const LAS float* Bf = (const LAS float*)(lds + L_BD); const LAS float* Bb = Bf + 64 * GS;
;     float kef[8], keb[8];
; #pragma unroll
;     for (int j = 0; j < 8; ++j) { const int d = dg * 8 + j; const float kv = (j & 1) ? bfhi(kk[j >> 1]) : bflo(kk[j >> 1]);
;       const float bl = Bf[63 * GS + d], b0 = Bb[d];
;       kef[j] = kv * __builtin_amdgcn_exp2f(bl - Bf[s * GS + d]); keb[j] = kv * __builtin_amdgcn_exp2f(b0 - Bb[s * GS + d]);
;       if (s == 0) { DEC[((size_t)(0 * NCHUNK + n) * 4 + h) * 64 + d] = __builtin_amdgcn_exp2f(bl); DEC[((size_t)(1 * NCHUNK + n) * 4 + h) * 64 + d] = __builtin_amdgcn_exp2f(b0); } }
.LBB0_217:
	s_ashr_i32 s28, s30, 2
	s_ashr_i32 s29, s28, 31
	s_and_b32 s33, s30, 3
	s_lshl_b64 s[0:1], s[28:29], 10
	s_add_u32 s0, s4, s0
	s_addc_u32 s1, s5, s1
	s_lshl_b32 s76, s33, 8
	v_and_b32_e32 v69, 7, v80
	s_add_u32 s30, s0, s76
	v_ashrrev_i32_e32 v68, 3, v80
	s_addc_u32 s31, s1, 0
	s_add_i32 s0, s28, 0x300
	v_lshl_add_u32 v2, v69, 5, 0
	s_waitcnt lgkmcnt(0)
	s_barrier
	s_ashr_i32 s1, s0, 31
	v_add_u32_e32 v66, 0x4200, v2
	v_mad_u64_u32 v[8:9], s[50:51], v68, s58, v[2:3]
	s_lshl_b64 s[48:49], s[0:1], 10
	ds_read2_b32 v[0:1], v66 offset0:60 offset1:128
	ds_read2st64_b32 v[2:3], v8 offset1:68
	s_add_u32 s48, s4, s48
	s_addc_u32 s49, s5, s49
	v_lshlrev_b32_e32 v4, 3, v69
	s_add_u32 s48, s48, s76
	v_cmp_gt_u32_e32 vcc, 8, v80
	s_addc_u32 s49, s49, 0
	v_lshlrev_b32_e32 v70, 2, v4
	s_and_saveexec_b64 s[50:51], vcc
	s_cbranch_execz .LBB0_219
	s_waitcnt lgkmcnt(1)
	v_exp_f32_e32 v4, v0
	v_exp_f32_e32 v5, v1
	global_store_dword v70, v4, s[30:31]
	global_store_dword v70, v5, s[48:49]

; __device__ __forceinline__ unsigned f2bf(float f) { unsigned u = __builtin_bit_cast(unsigned, f); return (u + 0x7fffu + ((u >> 16) & 1u)) >> 16; }
; __device__ __forceinline__ int crow(int r, int hi) { return (r & 3) + 8 * (r >> 2) + 4 * hi; }
; #define LBAR() do { asm volatile("s_waitcnt lgkmcnt(0)" ::: "memory"); __builtin_amdgcn_s_barrier(); asm volatile("" ::: "memory"); } while (0)
; __device__ __forceinline__ void g3_unit(const GPre& R, const float* __restrict__ gng, bf16* __restrict__ MIXIN, int n, int h, LAS char* lds) {
;     ...
;     LBAR();
;     const int e = 32 * et + r32; const float g = gng[e];
; #pragma unroll
;     for (int r = 0; r < 16; ++r) { const int cl = crow(r, hi), c = 32 * ct + cl;
;       const float tot = RS[(ct * 4 + 0) * 32 + cl] + RS[(ct * 4 + 1) * 32 + cl] + RS[(ct * 4 + 2) * 32 + cl] + RS[(ct * 4 + 3) * 32 + cl];
;       const float sc_ = 1.0f / sqrtf(tot * (1.0f / 128.0f) + EPS);
;       const float gr = bf2f(R.grv[r]);
;       const float sl = gr * __builtin_amdgcn_rcpf(1.0f + __builtin_amdgcn_exp2f(-1.4426950408889634f * gr));
;       MIXIN[(size_t)(row0 + c) * DM + 512 + h * 128 + e] = (bf16)f2bf(acc[r] * sc_ * g * sl); }
.LBB0_407:
	s_or_b64 exec, exec, s[0:1]
	v_or_b32_e32 v84, s6, v116
	s_waitcnt lgkmcnt(0)
	s_barrier
	s_waitcnt vmcnt(0)
	v_lshlrev_b32_e32 v85, 2, v84
	global_load_dword v112, v85, s[18:19]
	s_lshl_b32 s1, s5, 9
	s_add_i32 s1, s1, 0
	s_and_b32 s0, s15, 0xffffffc0
	v_lshlrev_b32_e32 v122, 16, v229
	v_lshl_add_u32 v85, v117, 2, s1
	s_add_i32 s3, s3, s0
	v_lshlrev_b32_e32 v184, 1, v84
	v_mul_f32_e32 v84, 0xbfb8aa3b, v122
	v_add_u32_e32 v113, 0x1e400, v85
	v_exp_f32_e32 v123, v84
	s_waitcnt lgkmcnt(3)
	v_or_b32_e32 v110, s3, v117
	ds_read_b128 v[100:103], v113
	ds_read_b128 v[84:87], v113 offset:32
	ds_read_b128 v[104:107], v113 offset:128
	ds_read_b128 v[88:91], v113 offset:160
	s_waitcnt lgkmcnt(4)
	ds_read_b128 v[114:117], v113 offset:256
	ds_read_b128 v[92:95], v113 offset:288
	ds_read_b128 v[118:121], v113 offset:384
	ds_read_b128 v[96:99], v113 offset:416
	s_waitcnt lgkmcnt(5)
	v_add_f32_e32 v100, v100, v104
	s_waitcnt lgkmcnt(3)
	v_add_f32_e32 v100, v100, v114
	v_add_f32_e32 v123, 1.0, v123
	s_waitcnt lgkmcnt(1)
	v_add_f32_e32 v100, v100, v118
	v_fmamk_f32 v100, v100, 0x3c000000, v191
	v_mul_f32_e32 v104, 0x4f800000, v100
	v_cmp_gt_f32_e32 vcc, s86, v100
	v_rcp_f32_e32 v123, v123
	v_add_f32_e32 v101, v101, v105
	v_cndmask_b32_e32 v100, v100, v104, vcc
	v_sqrt_f32_e32 v104, v100
	v_add_f32_e32 v101, v101, v115
	s_and_b32 s4, s29, 0x180
	v_mul_f32_e32 v114, v123, v122
	v_add_u32_e32 v115, -1, v104
	v_add_u32_e32 v118, 1, v104
	v_fma_f32 v123, -v115, v104, v100
	s_lshl_b32 s0, s4, 1
	v_fma_f32 v124, -v118, v104, v100
	v_cmp_ge_f32_e64 s[4:5], 0, v123
	s_add_u32 s0, s46, s0
	v_add_f32_e32 v101, v101, v119
	v_cndmask_b32_e64 v104, v104, v115, s[4:5]
	v_cmp_lt_f32_e64 s[4:5], 0, v124
	s_addc_u32 s1, s47, 0
	v_fmamk_f32 v101, v101, 0x3c000000, v191
	v_cndmask_b32_e64 v104, v104, v118, s[4:5]
	v_lshl_add_u64 v[108:109], s[0:1], 0, v[184:185]
	v_mul_f32_e32 v105, 0x4f800000, v101
	v_cmp_gt_f32_e64 s[0:1], s86, v101
	v_mul_f32_e32 v115, 0x37800000, v104
	v_cndmask_b32_e32 v104, v104, v115, vcc
	v_cndmask_b32_e64 v101, v101, v105, s[0:1]
	v_cmp_class_f32_e32 vcc, v100, v192
	v_sqrt_f32_e32 v105, v101
	v_ashrrev_i32_e32 v111, 31, v110
	v_cndmask_b32_e32 v100, v104, v100, vcc
	v_div_scale_f32 v104, s[4:5], v100, v100, 1.0
	v_rcp_f32_e32 v115, v104
	v_add_u32_e32 v119, -1, v105
	v_fma_f32 v125, -v119, v105, v101
	v_cmp_ge_f32_e32 vcc, 0, v125
	v_fma_f32 v123, -v104, v115, 1.0
	v_fmac_f32_e32 v115, v123, v115
	v_cndmask_b32_e32 v118, v105, v119, vcc
	v_div_scale_f32 v119, vcc, 1.0, v100, 1.0
	v_mul_f32_e32 v123, v119, v115
	v_fma_f32 v124, -v104, v123, v119
	v_fmac_f32_e32 v123, v124, v115
	v_fma_f32 v104, -v104, v123, v119
	v_div_fmas_f32 v104, v104, v115, v123
	v_div_fixup_f32 v100, v104, v100, 1.0
	v_mul_f32_e32 v0, v0, v100
	v_add_u32_e32 v122, 1, v105
	v_mov_b64_e32 v[134:135], v[42:43]
	v_mov_b64_e32 v[126:127], v[38:39]
	v_mov_b64_e32 v[130:131], v[46:47]
	s_add_i32 s15, s15, s28
	s_add_i32 s29, s29, s30
	v_mov_b32_e32 v229, v197
	v_mov_b32_e32 v230, v195
	v_mov_b64_e32 v[132:133], v[40:41]
	v_mov_b64_e32 v[124:125], v[36:37]
	v_mov_b64_e32 v[128:129], v[44:45]
	s_waitcnt vmcnt(0)
	v_mul_f32_e32 v0, v112, v0
	v_mul_f32_e32 v0, v114, v0
	v_bfe_u32 v100, v0, 16, 1
	v_add3_u32 v0, v0, v100, s81
	v_fma_f32 v100, -v122, v105, v101
	v_cmp_lt_f32_e32 vcc, 0, v100
	s_nop 1
	v_cndmask_b32_e32 v100, v118, v122, vcc
	v_mul_f32_e32 v104, 0x37800000, v100
	v_cndmask_b32_e64 v100, v100, v104, s[0:1]
	v_cmp_class_f32_e32 vcc, v101, v192
	s_nop 1
	v_cndmask_b32_e32 v104, v100, v101, vcc
	v_div_scale_f32 v105, s[0:1], v104, v104, 1.0
	v_rcp_f32_e32 v114, v105
	v_lshlrev_b64 v[100:101], 11, v[110:111]
	v_lshl_add_u64 v[100:101], v[108:109], 0, v[100:101]
	global_store_short_d16_hi v[100:101], v0, off offset:1024
	v_lshlrev_b32_e32 v101, 16, v228
	v_fma_f32 v0, -v105, v114, 1.0
	v_mul_f32_e32 v111, 0xbfb8aa3b, v101
	v_fmac_f32_e32 v114, v0, v114
	v_div_scale_f32 v0, vcc, 1.0, v104, 1.0
	v_exp_f32_e32 v111, v111
	v_mul_f32_e32 v100, v0, v114
	v_fma_f32 v115, -v105, v100, v0
	v_fmac_f32_e32 v100, v115, v114
	v_fma_f32 v0, -v105, v100, v0
	v_add_f32_e32 v105, 1.0, v111
	v_rcp_f32_e32 v105, v105
	v_div_fmas_f32 v0, v0, v114, v100
	v_div_fixup_f32 v0, v0, v104, 1.0
	v_mul_f32_e32 v0, v1, v0
	v_mul_f32_e32 v100, v105, v101
	v_mul_f32_e32 v0, v112, v0
	v_mul_f32_e32 v0, v100, v0
	v_add_f32_e32 v100, v102, v106
	v_add_f32_e32 v100, v100, v116
	v_add_f32_e32 v100, v100, v120
	v_fmamk_f32 v100, v100, 0x3c000000, v191
	v_mul_f32_e32 v101, 0x4f800000, v100
	v_cmp_gt_f32_e32 vcc, s86, v100
	v_bfe_u32 v1, v0, 16, 1
	v_add3_u32 v102, v0, v1, s81
	v_cndmask_b32_e32 v100, v100, v101, vcc
	v_sqrt_f32_e32 v101, v100
	v_or_b32_e32 v0, 1, v110
	v_ashrrev_i32_e32 v1, 31, v0
	v_lshlrev_b64 v[0:1], 11, v[0:1]
	v_add_u32_e32 v104, -1, v101
	v_fma_f32 v105, -v104, v101, v100
	v_cmp_ge_f32_e64 s[0:1], 0, v105
	v_add_u32_e32 v105, 1, v101
	v_lshl_add_u64 v[0:1], v[108:109], 0, v[0:1]
	v_cndmask_b32_e64 v104, v101, v104, s[0:1]
	v_fma_f32 v101, -v105, v101, v100
	v_cmp_lt_f32_e64 s[0:1], 0, v101
	global_store_short_d16_hi v[0:1], v102, off offset:1024
	v_lshlrev_b32_e32 v102, 16, v227
	v_cndmask_b32_e64 v101, v104, v105, s[0:1]
	v_mul_f32_e32 v104, 0x37800000, v101
	v_cndmask_b32_e32 v101, v101, v104, vcc
	v_cmp_class_f32_e32 vcc, v100, v192
	v_mul_f32_e32 v105, 0xbfb8aa3b, v102
	v_exp_f32_e32 v105, v105
	v_cndmask_b32_e32 v100, v101, v100, vcc
	v_div_scale_f32 v101, s[0:1], v100, v100, 1.0
	v_rcp_f32_e32 v104, v101
	v_mov_b32_e32 v227, v199
	v_mov_b32_e32 v228, v198
	v_fma_f32 v0, -v101, v104, 1.0
	v_fmac_f32_e32 v104, v0, v104
	v_div_scale_f32 v0, vcc, 1.0, v100, 1.0
	v_mul_f32_e32 v1, v0, v104
; __device__ __forceinline__ unsigned f2bf(float f) { unsigned u = __builtin_bit_cast(unsigned, f); return (u + 0x7fffu + ((u >> 16) & 1u)) >> 16; }
; __device__ __forceinline__ int crow(int r, int hi) { return (r & 3) + 8 * (r >> 2) + 4 * hi; }
; __device__ __forceinline__ void g3_unit(const GPre& R, const float* __restrict__ gng, bf16* __restrict__ MIXIN, int n, int h, LAS char* lds) {
;     ...
; #pragma unroll
;     for (int r = 0; r < 16; ++r) { const int cl = crow(r, hi), c = 32 * ct + cl;
;       const float tot = RS[(ct * 4 + 0) * 32 + cl] + RS[(ct * 4 + 1) * 32 + cl] + RS[(ct * 4 + 2) * 32 + cl] + RS[(ct * 4 + 3) * 32 + cl];
;       const float sc_ = 1.0f / sqrtf(tot * (1.0f / 128.0f) + EPS);
;       const float gr = bf2f(R.grv[r]);
;       const float sl = gr * __builtin_amdgcn_rcpf(1.0f + __builtin_amdgcn_exp2f(-1.4426950408889634f * gr));
;       MIXIN[(size_t)(row0 + c) * DM + 512 + h * 128 + e] = (bf16)f2bf(acc[r] * sc_ * g * sl); }
	v_fma_f32 v106, -v101, v1, v0
	v_fmac_f32_e32 v1, v106, v104
	v_fma_f32 v0, -v101, v1, v0
	v_div_fmas_f32 v0, v0, v104, v1
	v_div_fixup_f32 v0, v0, v100, 1.0
	v_mul_f32_e32 v0, v2, v0
	v_add_f32_e32 v2, v103, v107
	v_add_f32_e32 v2, v2, v117
	v_add_f32_e32 v2, v2, v121
	v_fmamk_f32 v2, v2, 0x3c000000, v191
	v_mul_f32_e32 v100, 0x4f800000, v2
	v_cmp_gt_f32_e32 vcc, s86, v2
	v_add_f32_e32 v101, 1.0, v105
	v_rcp_f32_e32 v101, v101
	v_cndmask_b32_e32 v2, v2, v100, vcc
	v_sqrt_f32_e32 v100, v2
	v_mul_f32_e32 v0, v112, v0
	v_mul_f32_e32 v1, v101, v102
	v_mul_f32_e32 v0, v1, v0
	v_add_u32_e32 v102, -1, v100
	v_fma_f32 v103, -v102, v100, v2
	v_cmp_ge_f32_e64 s[0:1], 0, v103
	v_add_u32_e32 v103, 1, v100
	v_bfe_u32 v1, v0, 16, 1
	v_cndmask_b32_e64 v102, v100, v102, s[0:1]
	v_fma_f32 v100, -v103, v100, v2
	v_cmp_lt_f32_e64 s[0:1], 0, v100
	v_add3_u32 v101, v0, v1, s81
	v_or_b32_e32 v0, 2, v110
	v_cndmask_b32_e64 v100, v102, v103, s[0:1]
	v_mul_f32_e32 v102, 0x37800000, v100
	v_cndmask_b32_e32 v100, v100, v102, vcc
	v_cmp_class_f32_e32 vcc, v2, v192
	v_ashrrev_i32_e32 v1, 31, v0
	v_lshlrev_b64 v[0:1], 11, v[0:1]
	v_cndmask_b32_e32 v2, v100, v2, vcc
	v_div_scale_f32 v100, s[0:1], v2, v2, 1.0
	v_rcp_f32_e32 v102, v100
	v_lshl_add_u64 v[0:1], v[108:109], 0, v[0:1]
	global_store_short_d16_hi v[0:1], v101, off offset:1024
	v_lshlrev_b32_e32 v101, 16, v226
	v_fma_f32 v0, -v100, v102, 1.0
	v_fmac_f32_e32 v102, v0, v102
	v_div_scale_f32 v0, vcc, 1.0, v2, 1.0
	v_mul_f32_e32 v1, v0, v102
	v_fma_f32 v104, -v100, v1, v0
	v_fmac_f32_e32 v1, v104, v102
	v_fma_f32 v0, -v100, v1, v0
	v_div_fmas_f32 v0, v0, v102, v1
	v_div_fixup_f32 v0, v0, v2, 1.0
	v_add_f32_e32 v2, v84, v88
	v_add_f32_e32 v2, v2, v92
	s_waitcnt lgkmcnt(0)
	v_add_f32_e32 v2, v2, v96
	v_fmamk_f32 v2, v2, 0x3c000000, v191
	v_mul_f32_e32 v0, v3, v0
	v_mul_f32_e32 v3, 0x4f800000, v2
	v_cmp_gt_f32_e32 vcc, s86, v2
	v_mul_f32_e32 v103, 0xbfb8aa3b, v101
	v_exp_f32_e32 v103, v103
	v_cndmask_b32_e32 v2, v2, v3, vcc
	v_sqrt_f32_e32 v3, v2
	v_mul_f32_e32 v0, v112, v0
	v_add_f32_e32 v100, 1.0, v103
	v_rcp_f32_e32 v100, v100
	v_add_u32_e32 v88, -1, v3
	v_fma_f32 v92, -v88, v3, v2
	v_cmp_ge_f32_e64 s[0:1], 0, v92
	v_add_u32_e32 v92, 1, v3
	v_mul_f32_e32 v1, v100, v101
	v_cndmask_b32_e64 v88, v3, v88, s[0:1]
	v_fma_f32 v3, -v92, v3, v2
	v_cmp_lt_f32_e64 s[0:1], 0, v3
	v_mul_f32_e32 v0, v1, v0
	v_bfe_u32 v1, v0, 16, 1
	v_cndmask_b32_e64 v3, v88, v92, s[0:1]
	v_mul_f32_e32 v88, 0x37800000, v3
	v_cndmask_b32_e32 v3, v3, v88, vcc
	v_cmp_class_f32_e32 vcc, v2, v192
	v_add3_u32 v84, v0, v1, s81
	v_or_b32_e32 v0, 3, v110
	v_cndmask_b32_e32 v2, v3, v2, vcc
	v_div_scale_f32 v3, s[0:1], v2, v2, 1.0
	v_rcp_f32_e32 v88, v3
	v_ashrrev_i32_e32 v1, 31, v0
	v_lshlrev_b64 v[0:1], 11, v[0:1]
	v_lshl_add_u64 v[0:1], v[108:109], 0, v[0:1]
	global_store_short_d16_hi v[0:1], v84, off offset:1024
	v_fma_f32 v0, -v3, v88, 1.0
	v_lshlrev_b32_e32 v84, 16, v225
	v_fmac_f32_e32 v88, v0, v88
	v_div_scale_f32 v0, vcc, 1.0, v2, 1.0
	v_mul_f32_e32 v92, 0xbfb8aa3b, v84
	v_mul_f32_e32 v1, v0, v88
	v_exp_f32_e32 v92, v92
	v_fma_f32 v96, -v3, v1, v0
	v_fmac_f32_e32 v1, v96, v88
	v_fma_f32 v0, -v3, v1, v0
	v_add_f32_e32 v3, 1.0, v92
	v_div_fmas_f32 v0, v0, v88, v1
	v_rcp_f32_e32 v3, v3
	v_div_fixup_f32 v0, v0, v2, 1.0
	v_add_f32_e32 v2, v85, v89
	v_add_f32_e32 v2, v2, v93
	v_add_f32_e32 v2, v2, v97
	v_fmamk_f32 v2, v2, 0x3c000000, v191
	v_mul_f32_e32 v1, v3, v84
	v_mul_f32_e32 v3, 0x4f800000, v2
	v_cmp_gt_f32_e32 vcc, s86, v2
	v_mul_f32_e32 v0, v4, v0
	v_mul_f32_e32 v0, v112, v0
	v_cndmask_b32_e32 v2, v2, v3, vcc
	v_sqrt_f32_e32 v3, v2
	v_mul_f32_e32 v0, v1, v0
	v_bfe_u32 v1, v0, 16, 1
	v_add3_u32 v4, v0, v1, s81
	v_add_u32_e32 v84, -1, v3
	v_fma_f32 v85, -v84, v3, v2
	v_cmp_ge_f32_e64 s[0:1], 0, v85
	v_add_u32_e32 v85, 1, v3
	v_or_b32_e32 v0, 8, v110
	v_cndmask_b32_e64 v84, v3, v84, s[0:1]
	v_fma_f32 v3, -v85, v3, v2
	v_cmp_lt_f32_e64 s[0:1], 0, v3
	v_ashrrev_i32_e32 v1, 31, v0
	v_lshlrev_b64 v[0:1], 11, v[0:1]
	v_cndmask_b32_e64 v3, v84, v85, s[0:1]
	v_mul_f32_e32 v84, 0x37800000, v3
	v_cndmask_b32_e32 v3, v3, v84, vcc
	v_cmp_class_f32_e32 vcc, v2, v192
	v_lshl_add_u64 v[0:1], v[108:109], 0, v[0:1]
	global_store_short_d16_hi v[0:1], v4, off offset:1024
	v_cndmask_b32_e32 v2, v3, v2, vcc
	v_div_scale_f32 v3, s[0:1], v2, v2, 1.0
	v_rcp_f32_e32 v84, v3
	v_lshlrev_b32_e32 v4, 16, v224
	v_mul_f32_e32 v85, 0xbfb8aa3b, v4
	v_exp_f32_e32 v85, v85
	v_fma_f32 v0, -v3, v84, 1.0
	v_fmac_f32_e32 v84, v0, v84
	v_div_scale_f32 v0, vcc, 1.0, v2, 1.0
	v_mul_f32_e32 v1, v0, v84
	v_fma_f32 v88, -v3, v1, v0
	v_fmac_f32_e32 v1, v88, v84
	v_fma_f32 v0, -v3, v1, v0
	v_add_f32_e32 v3, 1.0, v85
	v_div_fmas_f32 v0, v0, v84, v1
	v_rcp_f32_e32 v3, v3
	v_div_fixup_f32 v0, v0, v2, 1.0
	v_add_f32_e32 v2, v86, v90
	v_add_f32_e32 v2, v2, v94
	v_add_f32_e32 v2, v2, v98
	v_fmamk_f32 v2, v2, 0x3c000000, v191
	v_mul_f32_e32 v1, v3, v4
	v_mul_f32_e32 v3, 0x4f800000, v2
	v_cmp_gt_f32_e32 vcc, s86, v2
	v_mul_f32_e32 v0, v5, v0
	v_mul_f32_e32 v0, v112, v0
	v_cndmask_b32_e32 v2, v2, v3, vcc
	v_sqrt_f32_e32 v3, v2
	v_mul_f32_e32 v0, v1, v0
	v_bfe_u32 v1, v0, 16, 1
	v_add3_u32 v4, v0, v1, s81
	v_add_u32_e32 v5, -1, v3
	v_fma_f32 v84, -v5, v3, v2
	v_cmp_ge_f32_e64 s[0:1], 0, v84
	v_add_u32_e32 v84, 1, v3
	v_or_b32_e32 v0, 9, v110
	v_cndmask_b32_e64 v5, v3, v5, s[0:1]
	v_fma_f32 v3, -v84, v3, v2
	v_cmp_lt_f32_e64 s[0:1], 0, v3
	v_ashrrev_i32_e32 v1, 31, v0
	v_lshlrev_b64 v[0:1], 11, v[0:1]
	v_cndmask_b32_e64 v3, v5, v84, s[0:1]
	v_mul_f32_e32 v5, 0x37800000, v3
	v_cndmask_b32_e32 v3, v3, v5, vcc
	v_cmp_class_f32_e32 vcc, v2, v192
	v_lshl_add_u64 v[0:1], v[108:109], 0, v[0:1]
; __device__ __forceinline__ unsigned f2bf(float f) { unsigned u = __builtin_bit_cast(unsigned, f); return (u + 0x7fffu + ((u >> 16) & 1u)) >> 16; }
; __device__ __forceinline__ int crow(int r, int hi) { return (r & 3) + 8 * (r >> 2) + 4 * hi; }
; __device__ __forceinline__ void g3_unit(const GPre& R, const float* __restrict__ gng, bf16* __restrict__ MIXIN, int n, int h, LAS char* lds) {
;     ...
; #pragma unroll
;     for (int r = 0; r < 16; ++r) { const int cl = crow(r, hi), c = 32 * ct + cl;
;       const float tot = RS[(ct * 4 + 0) * 32 + cl] + RS[(ct * 4 + 1) * 32 + cl] + RS[(ct * 4 + 2) * 32 + cl] + RS[(ct * 4 + 3) * 32 + cl];
;       const float sc_ = 1.0f / sqrtf(tot * (1.0f / 128.0f) + EPS);
;       const float gr = bf2f(R.grv[r]);
;       const float sl = gr * __builtin_amdgcn_rcpf(1.0f + __builtin_amdgcn_exp2f(-1.4426950408889634f * gr));
;       MIXIN[(size_t)(row0 + c) * DM + 512 + h * 128 + e] = (bf16)f2bf(acc[r] * sc_ * g * sl); }
	global_store_short_d16_hi v[0:1], v4, off offset:1024
	v_cndmask_b32_e32 v2, v3, v2, vcc
	v_div_scale_f32 v3, s[0:1], v2, v2, 1.0
	v_rcp_f32_e32 v5, v3
	v_lshlrev_b32_e32 v4, 16, v223
	v_mul_f32_e32 v84, 0xbfb8aa3b, v4
	v_exp_f32_e32 v84, v84
	v_fma_f32 v0, -v3, v5, 1.0
	v_fmac_f32_e32 v5, v0, v5
	v_div_scale_f32 v0, vcc, 1.0, v2, 1.0
	v_mul_f32_e32 v1, v0, v5
	v_fma_f32 v85, -v3, v1, v0
	v_fmac_f32_e32 v1, v85, v5
	v_fma_f32 v0, -v3, v1, v0
	v_add_f32_e32 v3, 1.0, v84
	v_div_fmas_f32 v0, v0, v5, v1
	v_rcp_f32_e32 v3, v3
	v_div_fixup_f32 v0, v0, v2, 1.0
	v_add_f32_e32 v2, v87, v91
	v_add_f32_e32 v2, v2, v95
	v_add_f32_e32 v2, v2, v99
	v_fmamk_f32 v2, v2, 0x3c000000, v191
	v_mul_f32_e32 v1, v3, v4
	v_mul_f32_e32 v3, 0x4f800000, v2
	v_cmp_gt_f32_e32 vcc, s86, v2
	v_mul_f32_e32 v0, v6, v0
	v_mul_f32_e32 v0, v112, v0
	v_cndmask_b32_e32 v2, v2, v3, vcc
	v_sqrt_f32_e32 v3, v2
	v_mul_f32_e32 v0, v1, v0
	v_bfe_u32 v1, v0, 16, 1
	v_add3_u32 v4, v0, v1, s81
	v_add_u32_e32 v5, -1, v3
	v_fma_f32 v6, -v5, v3, v2
	v_cmp_ge_f32_e64 s[0:1], 0, v6
	v_add_u32_e32 v6, 1, v3
	v_or_b32_e32 v0, 10, v110
	v_cndmask_b32_e64 v5, v3, v5, s[0:1]
	v_fma_f32 v3, -v6, v3, v2
	v_cmp_lt_f32_e64 s[0:1], 0, v3
	v_ashrrev_i32_e32 v1, 31, v0
	v_lshlrev_b64 v[0:1], 11, v[0:1]
	v_cndmask_b32_e64 v3, v5, v6, s[0:1]
	v_mul_f32_e32 v5, 0x37800000, v3
	v_cndmask_b32_e32 v3, v3, v5, vcc
	v_cmp_class_f32_e32 vcc, v2, v192
	v_lshl_add_u64 v[0:1], v[108:109], 0, v[0:1]
	global_store_short_d16_hi v[0:1], v4, off offset:1024
	v_cndmask_b32_e32 v2, v3, v2, vcc
	v_div_scale_f32 v3, s[0:1], v2, v2, 1.0
	v_rcp_f32_e32 v5, v3
	v_lshlrev_b32_e32 v4, 16, v222
	v_mul_f32_e32 v6, 0xbfb8aa3b, v4
	v_exp_f32_e32 v6, v6
	v_fma_f32 v0, -v3, v5, 1.0
	v_fmac_f32_e32 v5, v0, v5
	v_div_scale_f32 v0, vcc, 1.0, v2, 1.0
	v_mul_f32_e32 v1, v0, v5
	v_fma_f32 v84, -v3, v1, v0
	v_fmac_f32_e32 v1, v84, v5
	v_fma_f32 v0, -v3, v1, v0
	v_add_f32_e32 v3, 1.0, v6
	v_rcp_f32_e32 v3, v3
	v_div_fmas_f32 v0, v0, v5, v1
	v_div_fixup_f32 v0, v0, v2, 1.0
	v_mul_f32_e32 v0, v7, v0
	v_mul_f32_e32 v1, v3, v4
	v_mul_f32_e32 v0, v112, v0
	v_mul_f32_e32 v111, v1, v0
	ds_read_b128 v[92:95], v113 offset:192
	ds_read_b128 v[96:99], v113 offset:64
	ds_read_b128 v[0:3], v113 offset:96
	ds_read_b128 v[100:103], v113 offset:320
	ds_read_b128 v[104:107], v113 offset:448
	ds_read_b128 v[4:7], v113 offset:224
	s_waitcnt lgkmcnt(4)
	v_add_f32_e32 v88, v96, v92
	v_bfe_u32 v114, v111, 16, 1
	s_waitcnt lgkmcnt(2)
	v_add_f32_e32 v92, v88, v100
	s_waitcnt lgkmcnt(1)
	v_add_f32_e32 v92, v92, v104
	v_fmamk_f32 v92, v92, 0x3c000000, v191
	v_mul_f32_e32 v96, 0x4f800000, v92
	v_cmp_gt_f32_e32 vcc, s86, v92
	v_add3_u32 v100, v111, v114, s81
	v_or_b32_e32 v114, 11, v110
	v_cndmask_b32_e32 v92, v92, v96, vcc
	v_sqrt_f32_e32 v96, v92
	v_ashrrev_i32_e32 v115, 31, v114
	v_lshlrev_b64 v[114:115], 11, v[114:115]
	ds_read_b128 v[84:87], v113 offset:352
	ds_read_b128 v[88:91], v113 offset:480
	v_add_u32_e32 v104, -1, v96
	v_fma_f32 v111, -v104, v96, v92
	v_cmp_ge_f32_e64 s[0:1], 0, v111
	v_add_u32_e32 v111, 1, v96
	v_lshl_add_u64 v[114:115], v[108:109], 0, v[114:115]
	v_cndmask_b32_e64 v104, v96, v104, s[0:1]
	v_fma_f32 v96, -v111, v96, v92
	v_cmp_lt_f32_e64 s[0:1], 0, v96
	v_lshlrev_b32_e32 v113, 16, v196
	global_store_short_d16_hi v[114:115], v100, off offset:1024
	v_cndmask_b32_e64 v96, v104, v111, s[0:1]
	v_mul_f32_e32 v104, 0x37800000, v96
	v_cndmask_b32_e32 v96, v96, v104, vcc
	v_cmp_class_f32_e32 vcc, v92, v192
	v_mul_f32_e32 v114, 0xbfb8aa3b, v113
	v_exp_f32_e32 v114, v114
	v_cndmask_b32_e32 v92, v96, v92, vcc
	v_div_scale_f32 v96, s[0:1], v92, v92, 1.0
	v_rcp_f32_e32 v104, v96
	v_add_f32_e32 v93, v97, v93
	v_add_f32_e32 v93, v93, v101
	v_add_f32_e32 v93, v93, v105
	v_fma_f32 v100, -v96, v104, 1.0
	v_fmac_f32_e32 v104, v100, v104
	v_div_scale_f32 v100, vcc, 1.0, v92, 1.0
	v_mul_f32_e32 v111, v100, v104
	v_fma_f32 v115, -v96, v111, v100
	v_fmac_f32_e32 v111, v115, v104
	v_fma_f32 v96, -v96, v111, v100
	v_add_f32_e32 v100, 1.0, v114
	v_rcp_f32_e32 v100, v100
	v_div_fmas_f32 v96, v96, v104, v111
	v_div_fixup_f32 v92, v96, v92, 1.0
	v_mul_f32_e32 v8, v8, v92
	v_mul_f32_e32 v96, v100, v113
	v_mul_f32_e32 v8, v112, v8
	v_fmamk_f32 v93, v93, 0x3c000000, v191
	v_mul_f32_e32 v8, v96, v8
	v_mul_f32_e32 v96, 0x4f800000, v93
	v_cmp_gt_f32_e32 vcc, s86, v93
	v_bfe_u32 v92, v8, 16, 1
	v_add3_u32 v8, v8, v92, s81
	v_cndmask_b32_e32 v96, v93, v96, vcc
	v_sqrt_f32_e32 v97, v96
	v_or_b32_e32 v92, 16, v110
	v_ashrrev_i32_e32 v93, 31, v92
	v_lshlrev_b64 v[92:93], 11, v[92:93]
	v_add_u32_e32 v100, -1, v97
	v_fma_f32 v101, -v100, v97, v96
	v_cmp_ge_f32_e64 s[0:1], 0, v101
	v_add_u32_e32 v101, 1, v97
	v_lshl_add_u64 v[92:93], v[108:109], 0, v[92:93]
	v_cndmask_b32_e64 v100, v97, v100, s[0:1]
	v_fma_f32 v97, -v101, v97, v96
	v_cmp_lt_f32_e64 s[0:1], 0, v97
	global_store_short_d16_hi v[92:93], v8, off offset:1024
	v_lshlrev_b32_e32 v93, 16, v194
	v_cndmask_b32_e64 v97, v100, v101, s[0:1]
	v_mul_f32_e32 v100, 0x37800000, v97
	v_cndmask_b32_e32 v97, v97, v100, vcc
	v_cmp_class_f32_e32 vcc, v96, v192
	v_mul_f32_e32 v101, 0xbfb8aa3b, v93
	v_exp_f32_e32 v101, v101
	v_cndmask_b32_e32 v96, v97, v96, vcc
	v_div_scale_f32 v97, s[0:1], v96, v96, 1.0
	v_rcp_f32_e32 v100, v97
	s_waitcnt lgkmcnt(2)
	v_add_f32_e32 v0, v0, v4
	s_waitcnt lgkmcnt(1)
	v_add_f32_e32 v0, v0, v84
	s_waitcnt lgkmcnt(0)
; __device__ __forceinline__ unsigned f2bf(float f) { unsigned u = __builtin_bit_cast(unsigned, f); return (u + 0x7fffu + ((u >> 16) & 1u)) >> 16; }
; __device__ __forceinline__ int crow(int r, int hi) { return (r & 3) + 8 * (r >> 2) + 4 * hi; }
; __device__ __forceinline__ void g3_unit(const GPre& R, const float* __restrict__ gng, bf16* __restrict__ MIXIN, int n, int h, LAS char* lds) {
;     ...
; #pragma unroll
;     for (int r = 0; r < 16; ++r) { const int cl = crow(r, hi), c = 32 * ct + cl;
;       const float tot = RS[(ct * 4 + 0) * 32 + cl] + RS[(ct * 4 + 1) * 32 + cl] + RS[(ct * 4 + 2) * 32 + cl] + RS[(ct * 4 + 3) * 32 + cl];
;       const float sc_ = 1.0f / sqrtf(tot * (1.0f / 128.0f) + EPS);
;       const float gr = bf2f(R.grv[r]);
;       const float sl = gr * __builtin_amdgcn_rcpf(1.0f + __builtin_amdgcn_exp2f(-1.4426950408889634f * gr));
;       MIXIN[(size_t)(row0 + c) * DM + 512 + h * 128 + e] = (bf16)f2bf(acc[r] * sc_ * g * sl); }
	v_add_f32_e32 v0, v0, v88
	v_fma_f32 v8, -v97, v100, 1.0
	v_fmac_f32_e32 v100, v8, v100
	v_div_scale_f32 v8, vcc, 1.0, v96, 1.0
	v_mul_f32_e32 v92, v8, v100
	v_fma_f32 v104, -v97, v92, v8
	v_fmac_f32_e32 v92, v104, v100
	v_fma_f32 v8, -v97, v92, v8
	v_add_f32_e32 v97, 1.0, v101
	v_rcp_f32_e32 v97, v97
	v_div_fmas_f32 v8, v8, v100, v92
	v_div_fixup_f32 v8, v8, v96, 1.0
	v_mul_f32_e32 v8, v9, v8
	v_mul_f32_e32 v92, v97, v93
	v_mul_f32_e32 v8, v112, v8
	v_mul_f32_e32 v8, v92, v8
	v_add_f32_e32 v92, v98, v94
	v_add_f32_e32 v92, v92, v102
	v_add_f32_e32 v92, v92, v106
	v_fmamk_f32 v92, v92, 0x3c000000, v191
	v_mul_f32_e32 v93, 0x4f800000, v92
	v_cmp_gt_f32_e32 vcc, s86, v92
	v_bfe_u32 v9, v8, 16, 1
	v_add3_u32 v94, v8, v9, s81
	v_cndmask_b32_e32 v92, v92, v93, vcc
	v_sqrt_f32_e32 v93, v92
	v_or_b32_e32 v8, 17, v110
	v_ashrrev_i32_e32 v9, 31, v8
	v_lshlrev_b64 v[8:9], 11, v[8:9]
	v_add_u32_e32 v96, -1, v93
	v_fma_f32 v97, -v96, v93, v92
	v_cmp_ge_f32_e64 s[0:1], 0, v97
	v_add_u32_e32 v97, 1, v93
	v_lshl_add_u64 v[8:9], v[108:109], 0, v[8:9]
	v_cndmask_b32_e64 v96, v93, v96, s[0:1]
	v_fma_f32 v93, -v97, v93, v92
	v_cmp_lt_f32_e64 s[0:1], 0, v93
	global_store_short_d16_hi v[8:9], v94, off offset:1024
	v_lshlrev_b32_e32 v94, 16, v193
	v_cndmask_b32_e64 v93, v96, v97, s[0:1]
	v_mul_f32_e32 v96, 0x37800000, v93
	v_cndmask_b32_e32 v93, v93, v96, vcc
	v_cmp_class_f32_e32 vcc, v92, v192
	v_mul_f32_e32 v97, 0xbfb8aa3b, v94
	v_exp_f32_e32 v97, v97
	v_cndmask_b32_e32 v92, v93, v92, vcc
	v_div_scale_f32 v93, s[0:1], v92, v92, 1.0
	v_rcp_f32_e32 v96, v93
	v_fmamk_f32 v0, v0, 0x3c000000, v191
	v_mul_f32_e32 v4, 0x4f800000, v0
	v_add_f32_e32 v1, v1, v5
	v_fma_f32 v8, -v93, v96, 1.0
	v_fmac_f32_e32 v96, v8, v96
	v_div_scale_f32 v8, vcc, 1.0, v92, 1.0
	v_mul_f32_e32 v9, v8, v96
	v_fma_f32 v98, -v93, v9, v8
	v_fmac_f32_e32 v9, v98, v96
	v_fma_f32 v8, -v93, v9, v8
	v_div_fmas_f32 v8, v8, v96, v9
	v_div_fixup_f32 v8, v8, v92, 1.0
	v_mul_f32_e32 v8, v10, v8
	v_add_f32_e32 v10, v99, v95
	v_add_f32_e32 v10, v10, v103
	v_add_f32_e32 v10, v10, v107
	v_fmamk_f32 v10, v10, 0x3c000000, v191
	v_mul_f32_e32 v92, 0x4f800000, v10
	v_cmp_gt_f32_e32 vcc, s86, v10
	v_add_f32_e32 v93, 1.0, v97
	v_rcp_f32_e32 v93, v93
	v_cndmask_b32_e32 v10, v10, v92, vcc
	v_sqrt_f32_e32 v92, v10
	v_mul_f32_e32 v8, v112, v8
	v_mul_f32_e32 v9, v93, v94
	v_mul_f32_e32 v8, v9, v8
	v_add_u32_e32 v94, -1, v92
	v_fma_f32 v95, -v94, v92, v10
	v_cmp_ge_f32_e64 s[0:1], 0, v95
	v_add_u32_e32 v95, 1, v92
	v_bfe_u32 v9, v8, 16, 1
	v_cndmask_b32_e64 v94, v92, v94, s[0:1]
	v_fma_f32 v92, -v95, v92, v10
	v_cmp_lt_f32_e64 s[0:1], 0, v92
	v_add3_u32 v93, v8, v9, s81
	v_or_b32_e32 v8, 18, v110
	v_cndmask_b32_e64 v92, v94, v95, s[0:1]
	v_mul_f32_e32 v94, 0x37800000, v92
	v_cndmask_b32_e32 v92, v92, v94, vcc
	v_cmp_class_f32_e32 vcc, v10, v192
	v_ashrrev_i32_e32 v9, 31, v8
	v_lshlrev_b64 v[8:9], 11, v[8:9]
	v_cndmask_b32_e32 v10, v92, v10, vcc
	v_div_scale_f32 v92, s[0:1], v10, v10, 1.0
	v_rcp_f32_e32 v94, v92
	v_lshl_add_u64 v[8:9], v[108:109], 0, v[8:9]
	global_store_short_d16_hi v[8:9], v93, off offset:1024
	v_lshlrev_b32_e32 v93, 16, v190
	v_fma_f32 v8, -v92, v94, 1.0
	v_fmac_f32_e32 v94, v8, v94
	v_div_scale_f32 v8, vcc, 1.0, v10, 1.0
	v_mul_f32_e32 v9, v8, v94
	v_fma_f32 v96, -v92, v9, v8
	v_fmac_f32_e32 v9, v96, v94
	v_fma_f32 v8, -v92, v9, v8
	v_div_fmas_f32 v8, v8, v94, v9
	v_cmp_gt_f32_e32 vcc, s86, v0
	v_mul_f32_e32 v95, 0xbfb8aa3b, v93
	v_exp_f32_e32 v95, v95
	v_cndmask_b32_e32 v0, v0, v4, vcc
	v_sqrt_f32_e32 v4, v0
	v_div_fixup_f32 v8, v8, v10, 1.0
	v_mul_f32_e32 v8, v11, v8
	v_add_f32_e32 v92, 1.0, v95
	v_add_u32_e32 v11, -1, v4
	v_fma_f32 v84, -v11, v4, v0
	v_rcp_f32_e32 v92, v92
	v_cmp_ge_f32_e64 s[0:1], 0, v84
	v_add_u32_e32 v84, 1, v4
	v_mul_f32_e32 v8, v112, v8
	v_cndmask_b32_e64 v11, v4, v11, s[0:1]
	v_fma_f32 v4, -v84, v4, v0
	v_cmp_lt_f32_e64 s[0:1], 0, v4
	v_mul_f32_e32 v9, v92, v93
	v_mul_f32_e32 v8, v9, v8
	v_cndmask_b32_e64 v4, v11, v84, s[0:1]
	v_mul_f32_e32 v11, 0x37800000, v4
	v_cndmask_b32_e32 v4, v4, v11, vcc
	v_cmp_class_f32_e32 vcc, v0, v192
	v_bfe_u32 v9, v8, 16, 1
	v_add3_u32 v10, v8, v9, s81
	v_cndmask_b32_e32 v0, v4, v0, vcc
	v_or_b32_e32 v8, 19, v110
	v_div_scale_f32 v4, s[0:1], v0, v0, 1.0
	v_ashrrev_i32_e32 v9, 31, v8
	v_rcp_f32_e32 v11, v4
	v_lshlrev_b64 v[8:9], 11, v[8:9]
	v_lshl_add_u64 v[8:9], v[108:109], 0, v[8:9]
	global_store_short_d16_hi v[8:9], v10, off offset:1024
	v_lshlrev_b32_e32 v10, 16, v189
	v_fma_f32 v8, -v4, v11, 1.0
	v_mul_f32_e32 v84, 0xbfb8aa3b, v10
	v_fmac_f32_e32 v11, v8, v11
	v_div_scale_f32 v8, vcc, 1.0, v0, 1.0
	v_exp_f32_e32 v84, v84
	v_mul_f32_e32 v9, v8, v11
	v_fma_f32 v88, -v4, v9, v8
	v_fmac_f32_e32 v9, v88, v11
	v_fma_f32 v4, -v4, v9, v8
	v_add_f32_e32 v8, 1.0, v84
	v_add_f32_e32 v1, v1, v85
	v_rcp_f32_e32 v8, v8
	v_add_f32_e32 v1, v1, v89
	v_fmamk_f32 v1, v1, 0x3c000000, v191
	v_div_fmas_f32 v4, v4, v11, v9
	v_mul_f32_e32 v5, 0x4f800000, v1
	v_cmp_gt_f32_e32 vcc, s86, v1
	v_div_fixup_f32 v0, v4, v0, 1.0
	v_mul_f32_e32 v4, v8, v10
	v_cndmask_b32_e32 v5, v1, v5, vcc
	v_sqrt_f32_e32 v8, v5
	v_mul_f32_e32 v0, v12, v0
	v_mul_f32_e32 v0, v112, v0
	v_mul_f32_e32 v0, v4, v0
	v_add_u32_e32 v9, -1, v8
	v_fma_f32 v10, -v9, v8, v5
	v_cmp_ge_f32_e64 s[0:1], 0, v10
	v_add_u32_e32 v10, 1, v8
	v_bfe_u32 v4, v0, 16, 1
	v_cndmask_b32_e64 v9, v8, v9, s[0:1]
	v_fma_f32 v8, -v10, v8, v5
	v_cmp_lt_f32_e64 s[0:1], 0, v8
	v_add3_u32 v4, v0, v4, s81
	v_or_b32_e32 v0, 24, v110
; #define LAS __attribute__((address_space(3)))
; __device__ __forceinline__ unsigned f2bf(float f) { unsigned u = __builtin_bit_cast(unsigned, f); return (u + 0x7fffu + ((u >> 16) & 1u)) >> 16; }
; __device__ __forceinline__ int crow(int r, int hi) { return (r & 3) + 8 * (r >> 2) + 4 * hi; }
; #define LBAR() do { asm volatile("s_waitcnt lgkmcnt(0)" ::: "memory"); __builtin_amdgcn_s_barrier(); asm volatile("" ::: "memory"); } while (0)
; __device__ __forceinline__ void g3_unit(const GPre& R, const float* __restrict__ gng, bf16* __restrict__ MIXIN, int n, int h, LAS char* lds) {
;     ...
;     for (int r = 0; r < 16; ++r) { const int cl = crow(r, hi), c = 32 * ct + cl;
;       const float tot = RS[(ct * 4 + 0) * 32 + cl] + RS[(ct * 4 + 1) * 32 + cl] + RS[(ct * 4 + 2) * 32 + cl] + RS[(ct * 4 + 3) * 32 + cl];
;       const float sc_ = 1.0f / sqrtf(tot * (1.0f / 128.0f) + EPS);
;       const float gr = bf2f(R.grv[r]);
;       const float sl = gr * __builtin_amdgcn_rcpf(1.0f + __builtin_amdgcn_exp2f(-1.4426950408889634f * gr));
;       MIXIN[(size_t)(row0 + c) * DM + 512 + h * 128 + e] = (bf16)f2bf(acc[r] * sc_ * g * sl); }
;   }
;   LBAR();
; __global__ void __launch_bounds__(NWAVES * 64, 2) hymba_fwd(Args args) {
;     ...
;       for (; u < NCHUNK * 4; u += G) { const int un = u + G;
;         if (un < NCHUNK * 4) gla::load_pre<true>(nxt, PROJ, args, WGT, STATE, un >> 2, un & 3);
;         gla::g3_unit(cur, args.in[15], H, u >> 2, u & 3, (LAS char*)ldsl); cur = nxt; } }
	v_cndmask_b32_e64 v8, v9, v10, s[0:1]
	v_mul_f32_e32 v9, 0x37800000, v8
	v_cndmask_b32_e32 v8, v8, v9, vcc
	v_cmp_class_f32_e32 vcc, v5, v192
	v_ashrrev_i32_e32 v1, 31, v0
	v_lshlrev_b64 v[0:1], 11, v[0:1]
	v_cndmask_b32_e32 v5, v8, v5, vcc
	v_div_scale_f32 v8, s[0:1], v5, v5, 1.0
	v_rcp_f32_e32 v9, v8
	v_lshl_add_u64 v[0:1], v[108:109], 0, v[0:1]
	global_store_short_d16_hi v[0:1], v4, off offset:1024
	v_lshlrev_b32_e32 v4, 16, v188
	v_fma_f32 v0, -v8, v9, 1.0
	v_mul_f32_e32 v10, 0xbfb8aa3b, v4
	v_fmac_f32_e32 v9, v0, v9
	v_div_scale_f32 v0, vcc, 1.0, v5, 1.0
	v_exp_f32_e32 v10, v10
	v_mul_f32_e32 v1, v0, v9
	v_fma_f32 v11, -v8, v1, v0
	v_fmac_f32_e32 v1, v11, v9
	v_fma_f32 v0, -v8, v1, v0
	v_add_f32_e32 v8, 1.0, v10
	v_rcp_f32_e32 v8, v8
	v_add_f32_e32 v2, v2, v6
	v_add_f32_e32 v2, v2, v86
	v_add_f32_e32 v2, v2, v90
	v_fmamk_f32 v2, v2, 0x3c000000, v191
	v_div_fmas_f32 v0, v0, v9, v1
	v_mul_f32_e32 v1, v8, v4
	v_mul_f32_e32 v4, 0x4f800000, v2
	v_cmp_gt_f32_e32 vcc, s86, v2
	v_div_fixup_f32 v0, v0, v5, 1.0
	v_mul_f32_e32 v0, v13, v0
	v_cndmask_b32_e32 v2, v2, v4, vcc
	v_sqrt_f32_e32 v4, v2
	v_mul_f32_e32 v0, v112, v0
	v_mul_f32_e32 v0, v1, v0
	v_bfe_u32 v1, v0, 16, 1
	v_add_u32_e32 v6, -1, v4
	v_fma_f32 v8, -v6, v4, v2
	v_cmp_ge_f32_e64 s[0:1], 0, v8
	v_add_u32_e32 v8, 1, v4
	v_add3_u32 v5, v0, v1, s81
	v_cndmask_b32_e64 v6, v4, v6, s[0:1]
	v_fma_f32 v4, -v8, v4, v2
	v_cmp_lt_f32_e64 s[0:1], 0, v4
	v_or_b32_e32 v0, 25, v110
	v_ashrrev_i32_e32 v1, 31, v0
	v_cndmask_b32_e64 v4, v6, v8, s[0:1]
	v_mul_f32_e32 v6, 0x37800000, v4
	v_cndmask_b32_e32 v4, v4, v6, vcc
	v_cmp_class_f32_e32 vcc, v2, v192
	v_lshlrev_b64 v[0:1], 11, v[0:1]
	v_lshl_add_u64 v[0:1], v[108:109], 0, v[0:1]
	v_cndmask_b32_e32 v2, v4, v2, vcc
	v_div_scale_f32 v4, s[0:1], v2, v2, 1.0
	v_rcp_f32_e32 v6, v4
	global_store_short_d16_hi v[0:1], v5, off offset:1024
	v_lshlrev_b32_e32 v5, 16, v187
	v_mul_f32_e32 v8, 0xbfb8aa3b, v5
	v_fma_f32 v0, -v4, v6, 1.0
	v_fmac_f32_e32 v6, v0, v6
	v_div_scale_f32 v0, vcc, 1.0, v2, 1.0
	v_mul_f32_e32 v1, v0, v6
	v_fma_f32 v9, -v4, v1, v0
	v_fmac_f32_e32 v1, v9, v6
	v_fma_f32 v0, -v4, v1, v0
	v_div_fmas_f32 v0, v0, v6, v1
	v_div_fixup_f32 v0, v0, v2, 1.0
	v_add_f32_e32 v2, v3, v7
	v_exp_f32_e32 v8, v8
	v_add_f32_e32 v2, v2, v87
	v_add_f32_e32 v2, v2, v91
	v_fmamk_f32 v2, v2, 0x3c000000, v191
	v_mul_f32_e32 v3, 0x4f800000, v2
	v_cmp_gt_f32_e32 vcc, s86, v2
	v_add_f32_e32 v4, 1.0, v8
	v_rcp_f32_e32 v4, v4
	v_cndmask_b32_e32 v2, v2, v3, vcc
	v_sqrt_f32_e32 v3, v2
	v_mul_f32_e32 v0, v14, v0
	v_mul_f32_e32 v1, v4, v5
	v_mul_f32_e32 v0, v112, v0
	v_add_u32_e32 v5, -1, v3
	v_fma_f32 v6, -v5, v3, v2
	v_cmp_ge_f32_e64 s[0:1], 0, v6
	v_add_u32_e32 v6, 1, v3
	v_mul_f32_e32 v0, v1, v0
	v_cndmask_b32_e64 v5, v3, v5, s[0:1]
	v_fma_f32 v3, -v6, v3, v2
	v_cmp_lt_f32_e64 s[0:1], 0, v3
	v_bfe_u32 v1, v0, 16, 1
	v_add3_u32 v4, v0, v1, s81
	v_cndmask_b32_e64 v3, v5, v6, s[0:1]
	v_mul_f32_e32 v5, 0x37800000, v3
	v_cndmask_b32_e32 v3, v3, v5, vcc
	v_cmp_class_f32_e32 vcc, v2, v192
	v_or_b32_e32 v0, 26, v110
	v_ashrrev_i32_e32 v1, 31, v0
	v_cndmask_b32_e32 v2, v3, v2, vcc
	v_div_scale_f32 v3, s[0:1], v2, v2, 1.0
	v_rcp_f32_e32 v5, v3
	v_lshlrev_b64 v[0:1], 11, v[0:1]
	v_lshl_add_u64 v[0:1], v[108:109], 0, v[0:1]
	global_store_short_d16_hi v[0:1], v4, off offset:1024
	v_lshlrev_b32_e32 v4, 16, v186
	v_fma_f32 v0, -v3, v5, 1.0
	v_mul_f32_e32 v6, 0xbfb8aa3b, v4
	v_fmac_f32_e32 v5, v0, v5
	v_div_scale_f32 v0, vcc, 1.0, v2, 1.0
	v_exp_f32_e32 v6, v6
	v_mul_f32_e32 v1, v0, v5
	v_fma_f32 v7, -v3, v1, v0
	v_fmac_f32_e32 v1, v7, v5
	v_fma_f32 v0, -v3, v1, v0
	v_add_f32_e32 v3, 1.0, v6
	v_rcp_f32_e32 v3, v3
	v_div_fmas_f32 v0, v0, v5, v1
	v_div_fixup_f32 v0, v0, v2, 1.0
	v_mul_f32_e32 v0, v15, v0
	v_mul_f32_e32 v1, v3, v4
	v_mul_f32_e32 v0, v112, v0
	v_mul_f32_e32 v0, v1, v0
	v_bfe_u32 v1, v0, 16, 1
	v_add3_u32 v2, v0, v1, s81
	v_or_b32_e32 v0, 27, v110
	v_ashrrev_i32_e32 v1, 31, v0
	v_lshlrev_b64 v[0:1], 11, v[0:1]
	v_lshl_add_u64 v[0:1], v[108:109], 0, v[0:1]
	global_store_short_d16_hi v[0:1], v2, off offset:1024
	s_waitcnt lgkmcnt(0)
	s_barrier
	v_mov_b64_e32 v[94:95], v[26:27]
	v_mov_b64_e32 v[98:99], v[54:55]
	v_mov_b64_e32 v[118:119], v[30:31]
	v_mov_b64_e32 v[122:123], v[34:35]
	v_mov_b64_e32 v[102:103], v[50:51]
	v_mov_b64_e32 v[106:107], v[58:59]
	v_mov_b64_e32 v[110:111], v[62:63]
	v_mov_b64_e32 v[114:115], v[66:67]
	v_mov_b64_e32 v[0:1], v[68:69]
	v_mov_b64_e32 v[4:5], v[72:73]
	v_mov_b64_e32 v[12:13], v[76:77]
	v_mov_b64_e32 v[8:9], v[80:81]
	v_mov_b64_e32 v[86:87], v[18:19]
	v_mov_b64_e32 v[90:91], v[22:23]
	s_andn2_b64 vcc, exec, s[24:25]
	v_mov_b32_e32 v186, v221
	v_mov_b32_e32 v187, v220
	v_mov_b32_e32 v188, v219
	v_mov_b32_e32 v189, v209
	v_mov_b32_e32 v190, v208
	v_mov_b32_e32 v193, v207
	v_mov_b32_e32 v194, v206
	v_mov_b32_e32 v196, v205
	v_mov_b32_e32 v222, v204
	v_mov_b32_e32 v223, v203
	v_mov_b32_e32 v224, v202
	v_mov_b32_e32 v225, v201
	v_mov_b32_e32 v226, v200
	v_mov_b64_e32 v[92:93], v[24:25]
	v_mov_b64_e32 v[96:97], v[52:53]
	v_mov_b64_e32 v[116:117], v[28:29]
	v_mov_b64_e32 v[120:121], v[32:33]
	v_mov_b64_e32 v[100:101], v[48:49]
	v_mov_b64_e32 v[104:105], v[56:57]
	v_mov_b64_e32 v[108:109], v[60:61]
	v_mov_b64_e32 v[112:113], v[64:65]
	v_mov_b64_e32 v[2:3], v[70:71]
	v_mov_b64_e32 v[6:7], v[74:75]
	v_mov_b64_e32 v[14:15], v[78:79]
	v_mov_b64_e32 v[10:11], v[82:83]
	v_mov_b64_e32 v[84:85], v[16:17]
	v_mov_b64_e32 v[88:89], v[20:21]
	s_cbranch_vccz .LBB0_428

; #define LAS __attribute__((address_space(3)))
; __device__ __forceinline__ unsigned pk2(float lo, float hi) { return f2bf(lo) | (f2bf(hi) << 16); }
; #define LBAR() do { asm volatile("s_waitcnt lgkmcnt(0)" ::: "memory"); __builtin_amdgcn_s_barrier(); asm volatile("" ::: "memory"); } while (0)
; __device__ __forceinline__ void g3_unit(const GPre& R, const float* __restrict__ gng, bf16* __restrict__ MIXIN, int n, int h, LAS char* lds) {
;     ...
;   { const LAS float* Bf = (const LAS float*)(lds + L_BD); const LAS float* Bb = Bf + 64 * GS;
;     float qf[8], kf[8], qb[8], kb[8];
; #pragma unroll
;     for (int j = 0; j < 8; ++j) { const int d = dg * 8 + j; const float kv = (j & 1) ? bfhi(kk[j >> 1]) : bflo(kk[j >> 1]); const float qv = ((j & 1) ? bfhi(qq[j >> 1]) : bflo(qq[j >> 1])) * 0.125f;
;       const float bf_ = Bf[s * GS + d], bb_ = Bb[s * GS + d];
;       qf[j] = qv * __builtin_amdgcn_exp2f(bf_); kf[j] = kv * __builtin_amdgcn_exp2f(-bf_); qb[j] = qv * __builtin_amdgcn_exp2f(bb_); kb[j] = kv * __builtin_amdgcn_exp2f(-bb_); }
;     v4u w;
;     w.x = pk2(qf[0], qf[1]); w.y = pk2(qf[2], qf[3]); w.z = pk2(qf[4], qf[5]); w.w = pk2(qf[6], qf[7]); *(LAS v4u*)(lds + L_QTF + (s * ST72 + dg * 8) * 2) = w;
;     w.x = pk2(qb[0], qb[1]); w.y = pk2(qb[2], qb[3]); w.z = pk2(qb[4], qb[5]); w.w = pk2(qb[6], qb[7]); *(LAS v4u*)(lds + L_QTB + (s * ST72 + dg * 8) * 2) = w;
;     w.x = pk2(kf[0], kf[1]); w.y = pk2(kf[2], kf[3]); w.z = pk2(kf[4], kf[5]); w.w = pk2(kf[6], kf[7]); *(LAS v4u*)(lds + L_KTF + (s * ST72 + dg * 8) * 2) = w;
;     w.x = pk2(kb[0], kb[1]); w.y = pk2(kb[2], kb[3]); w.z = pk2(kb[4], kb[5]); w.w = pk2(kb[6], kb[7]); *(LAS v4u*)(lds + L_KTB + (s * ST72 + dg * 8) * 2) = w; }
;   LBAR();
.LBB0_426:
	v_ashrrev_i32_e32 v112, 3, v162
	v_and_b32_e32 v113, 7, v162
	v_mul_lo_u32 v0, v112, s65
	v_lshl_add_u32 v0, v113, 3, v0
	s_waitcnt lgkmcnt(0)
	s_barrier
	v_lshl_add_u32 v12, v0, 2, 0
	ds_read_b128 v[0:3], v12
	ds_read_b128 v[4:7], v12 offset:17408
	ds_read_b128 v[8:11], v12 offset:16
	ds_read_b128 v[12:15], v12 offset:17424
	s_add_i32 s26, 0, 0x15400
	s_add_i32 s27, 0, 0x17800
	s_waitcnt lgkmcnt(3)
	v_exp_f32_e32 v92, v0
	v_exp_f32_e32 v93, v2
	v_exp_f32_e64 v94, -v0
	v_exp_f32_e32 v0, v1
	v_exp_f32_e64 v98, -v1
	v_exp_f32_e32 v1, v3
	v_exp_f32_e64 v99, -v3
	s_waitcnt lgkmcnt(2)
	v_exp_f32_e32 v101, v7
	v_exp_f32_e64 v103, -v7
	s_waitcnt lgkmcnt(1)
	v_exp_f32_e32 v104, v9
	v_exp_f32_e32 v3, v10
	v_exp_f32_e64 v7, -v10
	v_exp_f32_e32 v105, v11
	v_exp_f32_e64 v107, -v11
	v_lshlrev_b32_e32 v11, 16, v89
	v_lshlrev_b32_e32 v10, 16, v88
	v_pk_mul_f32 v[10:11], v[10:11], s[50:51] op_sel_hi:[1,0]
	v_exp_f32_e64 v106, -v9
	s_waitcnt lgkmcnt(0)
	v_exp_f32_e32 v108, v13
	v_exp_f32_e64 v110, -v13
	v_exp_f32_e32 v9, v14
	v_exp_f32_e64 v13, -v14
	v_exp_f32_e32 v109, v15
	v_exp_f32_e64 v111, -v15
	v_and_b32_e32 v15, 0xffff0000, v89
	v_and_b32_e32 v14, 0xffff0000, v88
	v_pk_mul_f32 v[88:89], v[10:11], v[92:93]
	v_lshlrev_b32_e32 v93, 16, v91
	v_lshlrev_b32_e32 v92, 16, v90
	v_and_b32_e32 v91, 0xffff0000, v91
	v_and_b32_e32 v90, 0xffff0000, v90
	v_exp_f32_e64 v95, -v2
	v_exp_f32_e32 v2, v8
	v_pk_mul_f32 v[90:91], v[90:91], s[50:51] op_sel_hi:[1,0]
	v_pk_mul_f32 v[14:15], v[14:15], s[50:51] op_sel_hi:[1,0]
	v_pk_mul_f32 v[104:105], v[90:91], v[104:105]
	v_pk_mul_f32 v[0:1], v[14:15], v[0:1]
	v_bfe_u32 v114, v105, 16, 1
	v_pk_mul_f32 v[92:93], v[92:93], s[50:51] op_sel_hi:[1,0]
	v_add3_u32 v105, v105, v114, s81
	v_bfe_u32 v114, v88, 16, 1
	v_pk_mul_f32 v[2:3], v[92:93], v[2:3]
	v_bfe_u32 v115, v104, 16, 1
	v_bfe_u32 v117, v1, 16, 1
	v_bfe_u32 v118, v0, 16, 1
	v_add3_u32 v88, v88, v114, s81
	v_exp_f32_e32 v96, v4
	v_exp_f32_e32 v100, v5
	v_exp_f32_e32 v97, v6
	v_add3_u32 v0, v0, v118, s81
	v_add3_u32 v1, v1, v117, s81
	v_add3_u32 v104, v104, v115, s81
	v_bfe_u32 v115, v89, 16, 1
	v_bfe_u32 v117, v2, 16, 1
	v_bfe_u32 v118, v3, 16, 1
	v_lshrrev_b32_e32 v88, 16, v88
	v_exp_f32_e64 v102, -v5
	v_exp_f32_e64 v5, -v6
	v_exp_f32_e64 v6, -v8
	v_exp_f32_e32 v8, v12
	v_add3_u32 v3, v3, v118, s81
	v_add3_u32 v2, v2, v117, s81
	v_add3_u32 v89, v89, v115, s81
	v_and_or_b32 v0, v0, s80, v88
	v_mul_lo_u32 v88, v112, s82
	v_lshrrev_b32_e32 v89, 16, v89
	v_lshrrev_b32_e32 v2, 16, v2
	v_lshrrev_b32_e32 v3, 16, v3
	v_lshl_add_u32 v88, v113, 4, v88
	v_and_or_b32 v3, v105, s80, v3
	v_and_or_b32 v2, v104, s80, v2
	v_and_or_b32 v1, v1, s80, v89
	v_add_u32_e32 v89, s26, v88
	ds_write_b128 v89, v[0:3]
	v_pk_mul_f32 v[0:1], v[10:11], v[96:97]
	v_pk_mul_f32 v[2:3], v[14:15], v[100:101]
	v_pk_mul_f32 v[10:11], v[90:91], v[108:109]
	v_pk_mul_f32 v[8:9], v[92:93], v[8:9]
	v_bfe_u32 v14, v11, 16, 1
	v_bfe_u32 v15, v10, 16, 1
	v_bfe_u32 v89, v3, 16, 1
	v_bfe_u32 v90, v2, 16, 1
	v_add3_u32 v90, v2, v90, s81
	v_add3_u32 v89, v3, v89, s81
	v_add3_u32 v2, v10, v15, s81
	v_add3_u32 v3, v11, v14, s81
	v_bfe_u32 v10, v0, 16, 1
	v_bfe_u32 v11, v1, 16, 1
	v_bfe_u32 v14, v8, 16, 1
	v_bfe_u32 v15, v9, 16, 1
	v_add3_u32 v9, v9, v15, s81
	v_add3_u32 v8, v8, v14, s81
	v_add3_u32 v1, v1, v11, s81
	v_add3_u32 v0, v0, v10, s81
	v_lshrrev_b32_e32 v0, 16, v0
	v_lshrrev_b32_e32 v1, 16, v1
	v_lshrrev_b32_e32 v8, 16, v8
	v_lshrrev_b32_e32 v9, 16, v9
	v_and_or_b32 v3, v3, s80, v9
	v_and_or_b32 v2, v2, s80, v8
	v_and_or_b32 v1, v89, s80, v1
	v_and_or_b32 v0, v90, s80, v0
	v_add_u32_e32 v8, s27, v88
	ds_write_b128 v8, v[0:3]
	v_lshlrev_b32_e32 v9, 16, v85
	v_lshlrev_b32_e32 v8, 16, v84
	v_and_b32_e32 v11, 0xffff0000, v85
	v_and_b32_e32 v10, 0xffff0000, v84
	v_and_b32_e32 v85, 0xffff0000, v87
	v_and_b32_e32 v84, 0xffff0000, v86
	v_pk_mul_f32 v[2:3], v[98:99], v[10:11]
	v_lshlrev_b32_e32 v15, 16, v87
	v_lshlrev_b32_e32 v14, 16, v86
	v_pk_mul_f32 v[86:87], v[106:107], v[84:85]
	v_pk_mul_f32 v[0:1], v[94:95], v[8:9]
	v_pk_mul_f32 v[6:7], v[6:7], v[14:15]
	v_bfe_u32 v89, v87, 16, 1
	v_bfe_u32 v90, v86, 16, 1
	v_bfe_u32 v91, v3, 16, 1
	v_bfe_u32 v92, v2, 16, 1
	v_add3_u32 v92, v2, v92, s81
	v_add3_u32 v91, v3, v91, s81
	v_add3_u32 v2, v86, v90, s81
	v_add3_u32 v3, v87, v89, s81
	v_bfe_u32 v86, v0, 16, 1
	v_bfe_u32 v87, v1, 16, 1
	v_bfe_u32 v89, v6, 16, 1
	v_bfe_u32 v90, v7, 16, 1
	v_exp_f32_e64 v4, -v4
	v_exp_f32_e64 v12, -v12
	v_add3_u32 v7, v7, v90, s81
	v_add3_u32 v6, v6, v89, s81
	v_add3_u32 v1, v1, v87, s81
	v_add3_u32 v0, v0, v86, s81
	v_lshrrev_b32_e32 v0, 16, v0
	v_lshrrev_b32_e32 v1, 16, v1
	v_lshrrev_b32_e32 v6, 16, v6
	v_lshrrev_b32_e32 v7, 16, v7
	v_add_u32_e32 v86, 0, v88
	v_and_or_b32 v3, v3, s80, v7
	v_and_or_b32 v2, v2, s80, v6
	v_and_or_b32 v1, v91, s80, v1
	v_and_or_b32 v0, v92, s80, v0
	v_add_u32_e32 v6, 0x19c00, v86
	ds_write_b128 v6, v[0:3]
	v_pk_mul_f32 v[2:3], v[102:103], v[10:11]
	v_pk_mul_f32 v[6:7], v[110:111], v[84:85]
	s_ashr_i32 s4, s3, 6
	v_pk_mul_f32 v[0:1], v[4:5], v[8:9]
	v_pk_mul_f32 v[4:5], v[12:13], v[14:15]
	v_bfe_u32 v8, v7, 16, 1
	v_bfe_u32 v9, v6, 16, 1
	v_bfe_u32 v10, v3, 16, 1
	v_bfe_u32 v11, v2, 16, 1
	v_add3_u32 v11, v2, v11, s81
	v_add3_u32 v10, v3, v10, s81
	v_add3_u32 v2, v6, v9, s81
	v_add3_u32 v3, v7, v8, s81
	v_bfe_u32 v6, v0, 16, 1
	v_bfe_u32 v7, v1, 16, 1
	v_bfe_u32 v8, v4, 16, 1
	v_bfe_u32 v9, v5, 16, 1
	s_cmpk_lt_u32 s3, 0x100
	v_add3_u32 v5, v5, v9, s81
	v_add3_u32 v4, v4, v8, s81
	v_add3_u32 v1, v1, v7, s81
	v_add3_u32 v0, v0, v6, s81
	s_cselect_b64 s[0:1], -1, 0
	v_lshrrev_b32_e32 v0, 16, v0
	v_lshrrev_b32_e32 v1, 16, v1
	v_lshrrev_b32_e32 v4, 16, v4
	v_lshrrev_b32_e32 v5, 16, v5
	s_and_b64 s[72:73], s[0:1], exec
	v_and_or_b32 v3, v3, s80, v5
	v_and_or_b32 v2, v2, s80, v4
	v_and_or_b32 v1, v10, s80, v1
	v_and_or_b32 v0, v11, s80, v0
	v_add_u32_e32 v4, 0x1c000, v86
	s_cselect_b32 s5, 0x15400, s83
	s_cselect_b32 s6, 0x19c00, s84
	s_cselect_b32 s33, 0, 0x2400
	s_lshr_b32 s72, s3, 2
	v_and_b32_e32 v116, 31, v162
	ds_write_b128 v4, v[0:3]
	s_and_b32 s72, s72, 32
	v_lshrrev_b32_e32 v0, 2, v162
	v_or_b32_e32 v96, s72, v116
	v_and_b32_e32 v97, 8, v0
	s_add_i32 s5, s5, 0
	v_mad_u32_u24 v0, v96, s85, v97
	s_waitcnt lgkmcnt(0)
	s_barrier
; #define LAS __attribute__((address_space(3)))
; __device__ __forceinline__ unsigned f2bf(float f) { unsigned u = __builtin_bit_cast(unsigned, f); return (u + 0x7fffu + ((u >> 16) & 1u)) >> 16; }
; __device__ __forceinline__ int crow(int r, int hi) { return (r & 3) + 8 * (r >> 2) + 4 * hi; }
; #define LBAR() do { asm volatile("s_waitcnt lgkmcnt(0)" ::: "memory"); __builtin_amdgcn_s_barrier(); asm volatile("" ::: "memory"); } while (0)
; __device__ __forceinline__ void g3_unit(const GPre& R, const float* __restrict__ gng, bf16* __restrict__ MIXIN, int n, int h, LAS char* lds) {
;     ...
;   { const int dir = wid >> 2, ct = (wid >> 1) & 1, st = wid & 1; f32x16 acc = {};
;     lcp Q = lds + (dir ? L_QTB : L_QTF); lcp K = lds + (dir ? L_KTB : L_KTF);
; #pragma unroll
;     for (int ks = 0; ks < 4; ++ks) acc = __builtin_amdgcn_mfma_f32_32x32x16_bf16(frag(Q, 32 * ct, 16 * ks, lane), frag(K, 32 * st, 16 * ks, lane), acc, 0, 0, 0);
;     LAS bf16* ATT = (LAS bf16*)(lds + (dir ? L_ATTB : L_ATTF));
; #pragma unroll
;     for (int r = 0; r < 16; ++r) { const int c = 32 * ct + crow(r, hi), s_ = 32 * st + r32; const bool keep = dir ? (s_ > c) : (s_ <= c);
;       ATT[c * ST72 + s_] = (bf16)f2bf(keep ? acc[r] : 0.f); } }
;   LBAR();
	v_lshl_add_u32 v0, v0, 1, s5
	s_lshl_b32 s73, s4, 5
	ds_read_b128 v[0:3], v0
	v_and_or_b32 v98, s73, 32, v116
	s_add_i32 s6, s6, 0
	v_mad_u32_u24 v4, v98, s85, v97
	v_lshl_add_u32 v4, v4, 1, s6
	ds_read_b128 v[4:7], v4
	v_or_b32_e32 v88, 16, v97
	v_mad_u32_u24 v8, v96, s85, v88
	v_lshl_add_u32 v8, v8, 1, s5
	v_mad_u32_u24 v88, v98, s85, v88
	ds_read_b128 v[84:87], v8
	v_lshl_add_u32 v88, v88, 1, s6
	ds_read_b128 v[88:91], v88
	s_waitcnt lgkmcnt(2)
	v_mfma_f32_32x32x16_bf16 v[0:15], v[0:3], v[4:7], 0
	v_or_b32_e32 v99, 32, v97
	v_mad_u32_u24 v92, v96, s85, v99
	v_lshl_add_u32 v92, v92, 1, s5
	ds_read_b128 v[92:95], v92
	v_or_b32_e32 v97, 48, v97
	v_bfe_u32 v118, v162, 5, 1
	v_lshlrev_b32_e32 v117, 2, v118
	s_waitcnt lgkmcnt(1)
	v_mfma_f32_32x32x16_bf16 v[0:15], v[84:87], v[88:91], v[0:15]
	v_mad_u32_u24 v84, v98, s85, v99
	v_lshl_add_u32 v84, v84, 1, s6
	ds_read_b128 v[84:87], v84
	v_mad_u32_u24 v88, v96, s85, v97
	v_lshl_add_u32 v88, v88, 1, s5
	ds_read_b128 v[88:91], v88
	s_add_i32 s5, s33, 0
	s_waitcnt lgkmcnt(1)
	v_mfma_f32_32x32x16_bf16 v[0:15], v[92:95], v[84:87], v[0:15]
	v_mad_u32_u24 v84, v98, s85, v97
	v_lshl_add_u32 v84, v84, 1, s6
	ds_read_b128 v[84:87], v84
	s_and_b32 s6, s73, 0x60
	v_and_b32_e32 v100, 63, v162
	v_bfe_u32 v124, v100, 2, 2
	s_waitcnt lgkmcnt(0)
	v_mfma_f32_32x32x16_bf16 v[0:15], v[88:91], v[84:87], v[0:15]
	v_or_b32_e32 v84, s72, v117
	v_cmp_gt_u32_e32 vcc, v98, v84
	s_xor_b64 vcc, s[0:1], vcc
	v_lshlrev_b32_e32 v85, 1, v98
	s_nop 7
	v_cndmask_b32_e32 v0, 0, v0, vcc
	v_bfe_u32 v86, v0, 16, 1
	v_add3_u32 v0, v0, v86, s81
	v_mul_u32_u24_e32 v86, 0x90, v84
	v_add3_u32 v85, s5, v85, v86
	ds_write_b16_d16_hi v85, v0
	v_or_b32_e32 v0, 1, v84
	v_cmp_gt_u32_e32 vcc, v98, v0
	s_xor_b64 vcc, s[0:1], vcc
	s_ashr_i32 s5, s3, 8
	v_cndmask_b32_e32 v0, 0, v1, vcc
	v_bfe_u32 v1, v0, 16, 1
	v_add3_u32 v0, v0, v1, s81
	ds_write_b16_d16_hi v85, v0 offset:144
	v_or_b32_e32 v0, 2, v84
	v_cmp_gt_u32_e32 vcc, v98, v0
	s_xor_b64 vcc, s[0:1], vcc
	s_lshl_b32 s3, s5, 5
	v_cndmask_b32_e32 v0, 0, v2, vcc
	v_bfe_u32 v1, v0, 16, 1
	v_add3_u32 v0, v0, v1, s81
	ds_write_b16_d16_hi v85, v0 offset:288
	v_or_b32_e32 v0, 3, v84
	v_cmp_gt_u32_e32 vcc, v98, v0
	s_xor_b64 vcc, s[0:1], vcc
	s_nop 0
	v_cndmask_b32_e32 v0, 0, v3, vcc
	v_bfe_u32 v1, v0, 16, 1
	v_add3_u32 v0, v0, v1, s81
	ds_write_b16_d16_hi v85, v0 offset:432
	v_or_b32_e32 v0, 8, v84
	v_cmp_gt_u32_e32 vcc, v98, v0
	s_xor_b64 vcc, s[0:1], vcc
	s_nop 0
	v_cndmask_b32_e32 v0, 0, v4, vcc
	v_bfe_u32 v1, v0, 16, 1
	v_add3_u32 v0, v0, v1, s81
	ds_write_b16_d16_hi v85, v0 offset:1152
	v_or_b32_e32 v0, 9, v84
	v_cmp_gt_u32_e32 vcc, v98, v0
	s_xor_b64 vcc, s[0:1], vcc
	v_bfe_u32 v4, v162, 2, 4
	v_cndmask_b32_e32 v0, 0, v5, vcc
	v_bfe_u32 v1, v0, 16, 1
	v_add3_u32 v0, v0, v1, s81
	ds_write_b16_d16_hi v85, v0 offset:1296
	v_or_b32_e32 v0, 10, v84
	v_cmp_gt_u32_e32 vcc, v98, v0
	s_xor_b64 vcc, s[0:1], vcc
	v_and_b32_e32 v120, 8, v4
	v_cndmask_b32_e32 v0, 0, v6, vcc
	v_bfe_u32 v1, v0, 16, 1
	v_add3_u32 v0, v0, v1, s81
	ds_write_b16_d16_hi v85, v0 offset:1440
	v_or_b32_e32 v0, 11, v84
	v_cmp_gt_u32_e32 vcc, v98, v0
	s_xor_b64 vcc, s[0:1], vcc
	v_and_b32_e32 v133, 11, v4
	v_cndmask_b32_e32 v0, 0, v7, vcc
	v_bfe_u32 v1, v0, 16, 1
	v_add3_u32 v0, v0, v1, s81
	ds_write_b16_d16_hi v85, v0 offset:1584
	v_or_b32_e32 v0, 16, v84
	v_cmp_gt_u32_e32 vcc, v98, v0
	s_xor_b64 vcc, s[0:1], vcc
	v_or_b32_e32 v104, 16, v120
	v_cndmask_b32_e32 v0, 0, v8, vcc
	v_bfe_u32 v1, v0, 16, 1
	v_add3_u32 v0, v0, v1, s81
	ds_write_b16_d16_hi v85, v0 offset:2304
	v_or_b32_e32 v0, 17, v84
	v_cmp_gt_u32_e32 vcc, v98, v0
	s_xor_b64 vcc, s[0:1], vcc
	v_or_b32_e32 v135, v104, v124
	v_cndmask_b32_e32 v0, 0, v9, vcc
	v_bfe_u32 v1, v0, 16, 1
	v_add3_u32 v0, v0, v1, s81
	ds_write_b16_d16_hi v85, v0 offset:2448
	v_or_b32_e32 v0, 18, v84
	v_cmp_gt_u32_e32 vcc, v98, v0
	s_xor_b64 vcc, s[0:1], vcc
	v_or_b32_e32 v112, 32, v120
	v_cndmask_b32_e32 v0, 0, v10, vcc
	v_bfe_u32 v1, v0, 16, 1
	v_add3_u32 v0, v0, v1, s81
	ds_write_b16_d16_hi v85, v0 offset:2592
	v_or_b32_e32 v0, 19, v84
	v_cmp_gt_u32_e32 vcc, v98, v0
	s_xor_b64 vcc, s[0:1], vcc
	v_or_b32_e32 v137, v112, v124
	v_cndmask_b32_e32 v0, 0, v11, vcc
	v_bfe_u32 v1, v0, 16, 1
	v_add3_u32 v0, v0, v1, s81
	ds_write_b16_d16_hi v85, v0 offset:2736
	v_or_b32_e32 v0, 24, v84
	v_cmp_gt_u32_e32 vcc, v98, v0
	s_xor_b64 vcc, s[0:1], vcc
	v_or_b32_e32 v125, 48, v120
	v_cndmask_b32_e32 v0, 0, v12, vcc
	v_bfe_u32 v1, v0, 16, 1
	v_add3_u32 v0, v0, v1, s81
	ds_write_b16_d16_hi v85, v0 offset:3456
	v_or_b32_e32 v0, 25, v84
	v_cmp_gt_u32_e32 vcc, v98, v0
	s_xor_b64 vcc, s[0:1], vcc
	v_or_b32_e32 v138, v125, v124
	v_cndmask_b32_e32 v0, 0, v13, vcc
	v_bfe_u32 v1, v0, 16, 1
	v_add3_u32 v0, v0, v1, s81
	ds_write_b16_d16_hi v85, v0 offset:3600
	v_or_b32_e32 v0, 26, v84
	v_cmp_gt_u32_e32 vcc, v98, v0
	s_xor_b64 vcc, s[0:1], vcc
	s_nop 0
	v_cndmask_b32_e32 v0, 0, v14, vcc
	v_bfe_u32 v1, v0, 16, 1
	v_add3_u32 v0, v0, v1, s81
	ds_write_b16_d16_hi v85, v0 offset:3744
	v_or_b32_e32 v0, 27, v84
	v_cmp_gt_u32_e32 vcc, v98, v0
	s_xor_b64 vcc, s[0:1], vcc
	s_nop 0
	v_cndmask_b32_e32 v0, 0, v15, vcc
	v_bfe_u32 v1, v0, 16, 1
	v_add3_u32 v0, v0, v1, s81
	ds_write_b16_d16_hi v85, v0 offset:3888
	v_or_b32_e32 v0, s3, v116
	v_mul_lo_u32 v119, v0, s85
	v_lshlrev_b32_e32 v1, 2, v162
	v_and_b32_e32 v0, 16, v162
	v_and_b32_e32 v1, 12, v1
	v_add_lshl_u32 v128, v119, v120, 1
	s_waitcnt lgkmcnt(0)
	s_barrier
; #define LAS __attribute__((address_space(3)))
; __device__ __forceinline__ void g3_unit(const GPre& R, const float* __restrict__ gng, bf16* __restrict__ MIXIN, int n, int h, LAS char* lds) {
;     ...
;   { const int ct = wid >> 2, et = wid & 3; f32x16 acc = {};
; #pragma unroll
;     for (int dir = 0; dir < 2; ++dir) { lcp ATT = lds + (dir ? L_ATTB : L_ATTF); lcp Q = lds + (dir ? L_QTB : L_QTF); lcp S = lds + (dir ? L_SB : L_SF);
; #pragma unroll
;       for (int ks = 0; ks < 4; ++ks) { acc = __builtin_amdgcn_mfma_f32_32x32x16_bf16(frag(ATT, 32 * ct, 16 * ks, lane), trfrag(lds + L_V, VS, 16 * ks, 32 * et, lane), acc, 0, 0, 0);
;                                        acc = __builtin_amdgcn_mfma_f32_32x32x16_bf16(frag(Q, 32 * ct, 16 * ks, lane), trfrag(S, VS, 16 * ks, 32 * et, lane), acc, 0, 0, 0); } }
;     LAS float* RS = (LAS float*)(lds + L_RS);
;     float ssr[16];
; #pragma unroll
;     for (int r = 0; r < 16; ++r) { float ss = acc[r] * acc[r]; ss += __shfl_xor(ss, 1); ss += __shfl_xor(ss, 2); ss += __shfl_xor(ss, 4); ss += __shfl_xor(ss, 8); ss += __shfl_xor(ss, 16); ssr[r] = ss; }
	v_or3_b32 v0, v1, v0, s6
	v_add_u32_e32 v5, 0, v128
	v_lshl_add_u32 v132, v0, 1, 0
	ds_read_b128 v[0:3], v5
	v_mad_u32_u24 v4, v133, s58, v132
	ds_read_b64_tr_b16 v[84:85], v4 offset:34816
	ds_read_b64_tr_b16 v[86:87], v4 offset:35904
	ds_read_b64_tr_b16 v[88:89], v4 offset:52224
	ds_read_b64_tr_b16 v[90:91], v4 offset:53312
	ds_read_b128 v[92:95], v5 offset:9216
	v_add_u32_e32 v96, s26, v128
	ds_read_b128 v[96:99], v96
	s_waitcnt lgkmcnt(4)
	v_mfma_f32_32x32x16_bf16 v[0:15], v[0:3], v[84:87], 0
	v_add_lshl_u32 v134, v119, v104, 1
	v_add_u32_e32 v105, 0, v134
	ds_read_b128 v[100:103], v105
	v_add_lshl_u32 v136, v119, v112, 1
	v_add_u32_e32 v113, 0, v136
	v_add_lshl_u32 v119, v119, v125, 1
	v_add_u32_e32 v126, 0, v119
	s_waitcnt lgkmcnt(1)
	v_mfma_f32_32x32x16_bf16 v[0:15], v[96:99], v[88:91], v[0:15]
	v_mad_u32_u24 v98, v135, s58, v132
	ds_read_b64_tr_b16 v[88:89], v98 offset:34816
	ds_read_b64_tr_b16 v[90:91], v98 offset:35904
	ds_read_b64_tr_b16 v[96:97], v98 offset:52224
	ds_read_b64_tr_b16 v[98:99], v98 offset:53312
	ds_read_b128 v[104:107], v105 offset:9216
	ds_read_b128 v[108:111], v113
	v_add_u32_e32 v128, s27, v128
	v_cmp_lt_i32_e32 vcc, v252, v213
	s_waitcnt lgkmcnt(4)
	v_mfma_f32_32x32x16_bf16 v[0:15], v[100:103], v[88:91], v[0:15]
	v_add_u32_e32 v100, s26, v134
	ds_read_b128 v[100:103], v100
	s_waitcnt lgkmcnt(0)
	v_mfma_f32_32x32x16_bf16 v[0:15], v[100:103], v[96:99], v[0:15]
	v_mad_u32_u24 v102, v137, s58, v132
	ds_read_b64_tr_b16 v[96:97], v102 offset:34816
	ds_read_b64_tr_b16 v[98:99], v102 offset:35904
	ds_read_b64_tr_b16 v[100:101], v102 offset:52224
	ds_read_b64_tr_b16 v[102:103], v102 offset:53312
	ds_read_b128 v[112:115], v113 offset:9216
	ds_read_b128 v[120:123], v126
	s_waitcnt lgkmcnt(4)
	v_mfma_f32_32x32x16_bf16 v[0:15], v[108:111], v[96:99], v[0:15]
	v_add_u32_e32 v108, s26, v136
	ds_read_b128 v[108:111], v108
	s_waitcnt lgkmcnt(0)
	v_mfma_f32_32x32x16_bf16 v[0:15], v[108:111], v[100:103], v[0:15]
	v_mad_u32_u24 v110, v138, s58, v132
	ds_read_b64_tr_b16 v[100:101], v110 offset:34816
	ds_read_b64_tr_b16 v[102:103], v110 offset:35904
	ds_read_b64_tr_b16 v[108:109], v110 offset:52224
	ds_read_b64_tr_b16 v[110:111], v110 offset:53312
	ds_read_b128 v[124:127], v126 offset:9216
	ds_read_b128 v[128:131], v128
	s_waitcnt lgkmcnt(4)
	v_mfma_f32_32x32x16_bf16 v[0:15], v[120:123], v[100:103], v[0:15]
	v_add_u32_e32 v120, s26, v119
	ds_read_b128 v[120:123], v120
	s_waitcnt lgkmcnt(0)
	v_mfma_f32_32x32x16_bf16 v[0:15], v[120:123], v[108:111], v[0:15]
	v_add_u32_e32 v108, 0x11000, v132
	v_mfma_f32_32x32x16_bf16 v[0:15], v[92:95], v[84:87], v[0:15]
	v_mad_u32_u24 v86, v133, s58, v108
	ds_read_b64_tr_b16 v[84:85], v86
	ds_read_b64_tr_b16 v[86:87], v86 offset:1088
	v_add_u32_e32 v92, s27, v136
	s_waitcnt lgkmcnt(0)
	v_mfma_f32_32x32x16_bf16 v[0:15], v[128:131], v[84:87], v[0:15]
	v_add_u32_e32 v84, s27, v134
	ds_read_b128 v[84:87], v84
	v_mfma_f32_32x32x16_bf16 v[0:15], v[104:107], v[88:91], v[0:15]
	v_mad_u32_u24 v90, v135, s58, v108
	ds_read_b64_tr_b16 v[88:89], v90
	ds_read_b64_tr_b16 v[90:91], v90 offset:1088
	ds_read_b128 v[92:95], v92
	s_waitcnt lgkmcnt(1)
	v_mfma_f32_32x32x16_bf16 v[0:15], v[84:87], v[88:91], v[0:15]
	v_mad_u32_u24 v86, v137, s58, v108
	ds_read_b64_tr_b16 v[84:85], v86
	ds_read_b64_tr_b16 v[86:87], v86 offset:1088
	v_mad_u32_u24 v90, v138, s58, v108
	v_mfma_f32_32x32x16_bf16 v[0:15], v[112:115], v[96:99], v[0:15]
	s_waitcnt lgkmcnt(0)
	v_mfma_f32_32x32x16_bf16 v[0:15], v[92:95], v[84:87], v[0:15]
	v_add_u32_e32 v84, s27, v119
	ds_read_b128 v[84:87], v84
	ds_read_b64_tr_b16 v[88:89], v90
	ds_read_b64_tr_b16 v[90:91], v90 offset:1088
	v_mfma_f32_32x32x16_bf16 v[0:15], v[124:127], v[100:103], v[0:15]
	s_waitcnt lgkmcnt(0)
	v_mfma_f32_32x32x16_bf16 v[0:15], v[84:87], v[88:91], v[0:15]
	v_cndmask_b32_e32 v84, v211, v252, vcc
	v_lshlrev_b32_e32 v112, 2, v84
	v_cmp_lt_i32_e32 vcc, v253, v213
	s_nop 1
	v_cndmask_b32_e32 v84, v211, v253, vcc
	v_lshlrev_b32_e32 v119, 2, v84
	s_nop 4
	v_pk_mul_f32 v[88:89], v[2:3], v[2:3]
	ds_bpermute_b32 v88, v112, v88
	ds_bpermute_b32 v89, v112, v89
	v_cmp_lt_i32_e32 vcc, v254, v213
	v_pk_mul_f32 v[98:99], v[4:5], v[4:5]
	ds_bpermute_b32 v98, v112, v98
	v_cndmask_b32_e32 v84, v211, v254, vcc
	s_waitcnt lgkmcnt(1)
	v_pk_fma_f32 v[88:89], v[2:3], v[2:3], v[88:89]
	ds_bpermute_b32 v92, v119, v88
	ds_bpermute_b32 v93, v119, v89
	v_lshlrev_b32_e32 v122, 2, v84
	ds_bpermute_b32 v99, v112, v99
	v_cmp_lt_i32_e32 vcc, v212, v213
	v_pk_mul_f32 v[90:91], v[6:7], v[6:7]
	s_waitcnt lgkmcnt(1)
	v_pk_add_f32 v[88:89], v[88:89], v[92:93]
	ds_bpermute_b32 v92, v122, v88
	ds_bpermute_b32 v93, v122, v89
	v_cndmask_b32_e32 v84, v211, v212, vcc
	v_lshlrev_b32_e32 v123, 2, v84
	s_waitcnt lgkmcnt(2)
	v_pk_fma_f32 v[98:99], v[4:5], v[4:5], v[98:99]
	ds_bpermute_b32 v100, v119, v98
	s_waitcnt lgkmcnt(1)
	v_pk_add_f32 v[88:89], v[88:89], v[92:93]
	ds_bpermute_b32 v92, v123, v88
	ds_bpermute_b32 v93, v123, v89
	ds_bpermute_b32 v101, v119, v99
	v_pk_mul_f32 v[94:95], v[8:9], v[8:9]
	v_pk_mul_f32 v[96:97], v[10:11], v[10:11]
	ds_bpermute_b32 v110, v112, v96
	s_waitcnt lgkmcnt(2)
	v_pk_add_f32 v[88:89], v[88:89], v[92:93]
	ds_bpermute_b32 v92, v112, v90
	ds_bpermute_b32 v93, v112, v91
	s_waitcnt lgkmcnt(3)
; __device__ __forceinline__ int crow(int r, int hi) { return (r & 3) + 8 * (r >> 2) + 4 * hi; }
; #define LBAR() do { asm volatile("s_waitcnt lgkmcnt(0)" ::: "memory"); __builtin_amdgcn_s_barrier(); asm volatile("" ::: "memory"); } while (0)
; __device__ __forceinline__ void g3_unit(const GPre& R, const float* __restrict__ gng, bf16* __restrict__ MIXIN, int n, int h, LAS char* lds) {
;     ...
;     for (int r = 0; r < 16; ++r) { float ss = acc[r] * acc[r]; ss += __shfl_xor(ss, 1); ss += __shfl_xor(ss, 2); ss += __shfl_xor(ss, 4); ss += __shfl_xor(ss, 8); ss += __shfl_xor(ss, 16); ssr[r] = ss; }
;     if (r32 == 0) {
; #pragma unroll
;       for (int r = 0; r < 16; ++r) RS[wid * 32 + crow(r, hi)] = ssr[r]; }
;     LBAR();
	v_pk_add_f32 v[98:99], v[98:99], v[100:101]
	ds_bpermute_b32 v100, v122, v98
	ds_bpermute_b32 v101, v122, v99
	ds_bpermute_b32 v111, v112, v97
	s_waitcnt lgkmcnt(3)
	v_pk_fma_f32 v[92:93], v[6:7], v[6:7], v[92:93]
	ds_bpermute_b32 v102, v119, v92
	ds_bpermute_b32 v103, v119, v93
	s_waitcnt lgkmcnt(3)
	v_pk_add_f32 v[98:99], v[98:99], v[100:101]
	ds_bpermute_b32 v100, v123, v98
	ds_bpermute_b32 v101, v123, v99
	v_pk_mul_f32 v[84:85], v[0:1], v[0:1]
	s_waitcnt lgkmcnt(2)
	v_pk_add_f32 v[102:103], v[92:93], v[102:103]
	ds_bpermute_b32 v108, v122, v102
	ds_bpermute_b32 v109, v122, v103
	s_waitcnt lgkmcnt(2)
	v_pk_add_f32 v[92:93], v[98:99], v[100:101]
	ds_bpermute_b32 v98, v112, v94
	ds_bpermute_b32 v99, v112, v95
	v_pk_mul_f32 v[104:105], v[14:15], v[14:15]
	s_waitcnt lgkmcnt(2)
	v_pk_add_f32 v[100:101], v[102:103], v[108:109]
	ds_bpermute_b32 v102, v123, v100
	ds_bpermute_b32 v103, v123, v101
	s_waitcnt lgkmcnt(2)
	v_pk_fma_f32 v[98:99], v[8:9], v[8:9], v[98:99]
	ds_bpermute_b32 v108, v119, v98
	ds_bpermute_b32 v109, v119, v99
	v_pk_mul_f32 v[106:107], v[12:13], v[12:13]
	s_waitcnt lgkmcnt(2)
	v_pk_add_f32 v[96:97], v[100:101], v[102:103]
	ds_bpermute_b32 v84, v112, v84
	ds_bpermute_b32 v85, v112, v85
	s_waitcnt lgkmcnt(2)
	v_pk_add_f32 v[100:101], v[98:99], v[108:109]
	v_pk_fma_f32 v[108:109], v[10:11], v[10:11], v[110:111]
	ds_bpermute_b32 v110, v119, v108
	ds_bpermute_b32 v111, v119, v109
	ds_bpermute_b32 v106, v112, v106
	ds_bpermute_b32 v107, v112, v107
	ds_bpermute_b32 v104, v112, v104
	ds_bpermute_b32 v105, v112, v105
	s_waitcnt lgkmcnt(4)
	v_pk_add_f32 v[108:109], v[108:109], v[110:111]
	ds_bpermute_b32 v110, v122, v108
	ds_bpermute_b32 v111, v122, v109
	v_cmp_lt_i32_e32 vcc, v218, v213
	v_pk_fma_f32 v[84:85], v[0:1], v[0:1], v[84:85]
	s_waitcnt lgkmcnt(4)
	v_pk_fma_f32 v[106:107], v[12:13], v[12:13], v[106:107]
	v_cndmask_b32_e32 v86, v211, v218, vcc
	s_waitcnt lgkmcnt(0)
	v_pk_add_f32 v[108:109], v[108:109], v[110:111]
	v_pk_fma_f32 v[114:115], v[14:15], v[14:15], v[104:105]
	v_lshlrev_b32_e32 v124, 2, v86
	ds_bpermute_b32 v86, v119, v84
	ds_bpermute_b32 v87, v119, v85
	ds_bpermute_b32 v110, v123, v108
	ds_bpermute_b32 v111, v123, v109
	ds_bpermute_b32 v112, v119, v106
	ds_bpermute_b32 v113, v119, v107
	ds_bpermute_b32 v120, v119, v114
	ds_bpermute_b32 v121, v119, v115
	s_waitcnt lgkmcnt(6)
	v_pk_add_f32 v[84:85], v[84:85], v[86:87]
	s_waitcnt lgkmcnt(4)
	v_pk_add_f32 v[104:105], v[108:109], v[110:111]
	s_waitcnt lgkmcnt(2)
	v_pk_add_f32 v[108:109], v[106:107], v[112:113]
	ds_bpermute_b32 v86, v122, v84
	s_waitcnt lgkmcnt(1)
	v_pk_add_f32 v[112:113], v[114:115], v[120:121]
	ds_bpermute_b32 v87, v122, v85
	ds_bpermute_b32 v102, v122, v100
	ds_bpermute_b32 v103, v122, v101
	ds_bpermute_b32 v110, v122, v108
	ds_bpermute_b32 v111, v122, v109
	ds_bpermute_b32 v114, v122, v112
	ds_bpermute_b32 v115, v122, v113
	s_waitcnt lgkmcnt(6)
	v_pk_add_f32 v[84:85], v[84:85], v[86:87]
	s_waitcnt lgkmcnt(4)
	v_pk_add_f32 v[100:101], v[100:101], v[102:103]
	s_waitcnt lgkmcnt(2)
	v_pk_add_f32 v[108:109], v[108:109], v[110:111]
	ds_bpermute_b32 v86, v123, v84
	s_waitcnt lgkmcnt(1)
	v_pk_add_f32 v[112:113], v[112:113], v[114:115]
	ds_bpermute_b32 v87, v123, v85
	ds_bpermute_b32 v102, v123, v100
	ds_bpermute_b32 v103, v123, v101
	ds_bpermute_b32 v110, v123, v108
	ds_bpermute_b32 v111, v123, v109
	ds_bpermute_b32 v114, v123, v112
	ds_bpermute_b32 v115, v123, v113
	s_waitcnt lgkmcnt(6)
	v_pk_add_f32 v[84:85], v[84:85], v[86:87]
	s_waitcnt lgkmcnt(4)
	v_pk_add_f32 v[100:101], v[100:101], v[102:103]
	s_waitcnt lgkmcnt(2)
	v_pk_add_f32 v[108:109], v[108:109], v[110:111]
	ds_bpermute_b32 v86, v124, v84
	s_waitcnt lgkmcnt(1)
	v_pk_add_f32 v[112:113], v[112:113], v[114:115]
	ds_bpermute_b32 v87, v124, v85
	ds_bpermute_b32 v90, v124, v88
	ds_bpermute_b32 v91, v124, v89
	ds_bpermute_b32 v94, v124, v92
	ds_bpermute_b32 v95, v124, v93
	ds_bpermute_b32 v98, v124, v96
	ds_bpermute_b32 v99, v124, v97
	ds_bpermute_b32 v102, v124, v100
	ds_bpermute_b32 v103, v124, v101
	ds_bpermute_b32 v106, v124, v104
	ds_bpermute_b32 v107, v124, v105
	ds_bpermute_b32 v110, v124, v108
	ds_bpermute_b32 v111, v124, v109
	ds_bpermute_b32 v114, v124, v112
	ds_bpermute_b32 v115, v124, v113
	v_cmp_eq_u32_e32 vcc, 0, v116
	s_and_saveexec_b64 s[0:1], vcc
	s_cbranch_execz .LBB0_407
	s_lshl_b32 s4, s4, 7
	s_add_i32 s4, s4, 0
	v_lshl_add_u32 v118, v118, 4, s4
	v_add_u32_e32 v118, 0x1e400, v118
	s_waitcnt lgkmcnt(14)
	v_pk_add_f32 v[84:85], v[84:85], v[86:87]
	s_waitcnt lgkmcnt(12)
	v_pk_add_f32 v[86:87], v[88:89], v[90:91]
	ds_write_b128 v118, v[84:87]
	s_waitcnt lgkmcnt(11)
	v_pk_add_f32 v[84:85], v[92:93], v[94:95]
	s_waitcnt lgkmcnt(9)
	v_pk_add_f32 v[86:87], v[96:97], v[98:99]
	ds_write_b128 v118, v[84:87] offset:32
	s_waitcnt lgkmcnt(8)
	v_pk_add_f32 v[84:85], v[100:101], v[102:103]
	s_waitcnt lgkmcnt(6)
	v_pk_add_f32 v[86:87], v[104:105], v[106:107]
	ds_write_b128 v118, v[84:87] offset:64
	s_waitcnt lgkmcnt(5)
	v_pk_add_f32 v[84:85], v[108:109], v[110:111]
	s_waitcnt lgkmcnt(3)
	v_pk_add_f32 v[86:87], v[112:113], v[114:115]
	ds_write_b128 v118, v[84:87] offset:96
	s_branch .LBB0_407
